# K-loops: vmcnt/lgkmcnt waits before each barrier merged into one s_waitcnt and the redundant post-barrier lgkmcnt(0) dropped (36 sites) on v30
# baseline (speedup 1.0000x reference)
.LBB0_201:
	ds_read_b128 v[144:147], v155
	ds_read_b128 v[148:151], v155 offset:1024
	ds_read_b128 v[158:161], v155 offset:2048
	ds_read_b128 v[162:165], v155 offset:3072
	ds_read_b128 v[166:169], v156
	ds_read_b128 v[170:173], v156 offset:1024
	ds_read_b128 v[174:177], v156 offset:2048
	ds_read_b128 v[178:181], v156 offset:3072
	s_add_u32 s56, s54, 0xfffc0080
	s_addc_u32 s57, s55, -1
	s_cmp_eq_u32 s86, 12
	s_cselect_b32 s59, s11, s57
	s_cselect_b32 s58, s26, s56
	s_cselect_b32 s57, s27, s53
	s_cselect_b32 s56, s45, s47
	v_lshl_add_u64 v[214:215], s[54:55], 0, v[138:139]
	s_add_i32 m0, s63, 0xc000
	ds_read_b128 v[182:185], v157
	ds_read_b128 v[186:189], v157 offset:1024
	ds_read_b128 v[190:193], v157 offset:2048
	ds_read_b128 v[194:197], v157 offset:3072
	ds_read_b128 v[198:201], v157 offset:4096
	ds_read_b128 v[202:205], v157 offset:5120
	ds_read_b128 v[206:209], v157 offset:6144
	ds_read_b128 v[210:213], v157 offset:7168
	global_load_lds_dwordx4 v[214:215], off
	v_lshl_add_u64 v[214:215], s[54:55], 0, v[136:137]
	s_add_i32 m0, s63, 0xe000
	s_nop 0
	global_load_lds_dwordx4 v[214:215], off
	s_waitcnt vmcnt(8) lgkmcnt(0)
	s_barrier
	v_mfma_f32_16x16x32_bf16 v[124:127], v[144:147], v[182:185], v[124:127]
	v_mfma_f32_16x16x32_bf16 v[120:123], v[158:161], v[182:185], v[120:123]
	v_mfma_f32_16x16x32_bf16 v[108:111], v[144:147], v[190:193], v[108:111]
	v_mfma_f32_16x16x32_bf16 v[104:107], v[158:161], v[190:193], v[104:107]
	v_mfma_f32_16x16x32_bf16 v[92:95], v[144:147], v[198:201], v[92:95]
	v_mfma_f32_16x16x32_bf16 v[88:91], v[158:161], v[198:201], v[88:91]
	v_mfma_f32_16x16x32_bf16 v[76:79], v[144:147], v[206:209], v[76:79]
	v_mfma_f32_16x16x32_bf16 v[72:75], v[158:161], v[206:209], v[72:75]
	v_mfma_f32_16x16x32_bf16 v[124:127], v[148:151], v[186:189], v[124:127]
	v_mfma_f32_16x16x32_bf16 v[120:123], v[162:165], v[186:189], v[120:123]
	v_mfma_f32_16x16x32_bf16 v[108:111], v[148:151], v[194:197], v[108:111]
	v_mfma_f32_16x16x32_bf16 v[104:107], v[162:165], v[194:197], v[104:107]
	v_mfma_f32_16x16x32_bf16 v[92:95], v[148:151], v[202:205], v[92:95]
	v_mfma_f32_16x16x32_bf16 v[88:91], v[162:165], v[202:205], v[88:91]
	v_mfma_f32_16x16x32_bf16 v[76:79], v[148:151], v[210:213], v[76:79]
	v_mfma_f32_16x16x32_bf16 v[72:75], v[162:165], v[210:213], v[72:75]
	v_mfma_f32_16x16x32_bf16 v[116:119], v[166:169], v[182:185], v[116:119]
	v_mfma_f32_16x16x32_bf16 v[112:115], v[174:177], v[182:185], v[112:115]
	v_mfma_f32_16x16x32_bf16 v[100:103], v[166:169], v[190:193], v[100:103]
	v_mfma_f32_16x16x32_bf16 v[96:99], v[174:177], v[190:193], v[96:99]
	v_mfma_f32_16x16x32_bf16 v[84:87], v[166:169], v[198:201], v[84:87]
	v_mfma_f32_16x16x32_bf16 v[80:83], v[174:177], v[198:201], v[80:83]
	v_mfma_f32_16x16x32_bf16 v[68:71], v[166:169], v[206:209], v[68:71]
	v_mfma_f32_16x16x32_bf16 v[64:67], v[174:177], v[206:209], v[64:67]
	v_mfma_f32_16x16x32_bf16 v[116:119], v[170:173], v[186:189], v[116:119]
	v_mfma_f32_16x16x32_bf16 v[112:115], v[178:181], v[186:189], v[112:115]
	v_mfma_f32_16x16x32_bf16 v[100:103], v[170:173], v[194:197], v[100:103]
	v_mfma_f32_16x16x32_bf16 v[96:99], v[178:181], v[194:197], v[96:99]
	v_mfma_f32_16x16x32_bf16 v[84:87], v[170:173], v[202:205], v[84:87]
	v_mfma_f32_16x16x32_bf16 v[80:83], v[178:181], v[202:205], v[80:83]
	v_mfma_f32_16x16x32_bf16 v[68:71], v[170:173], v[210:213], v[68:71]
	v_mfma_f32_16x16x32_bf16 v[64:67], v[178:181], v[210:213], v[64:67]
	s_barrier
	s_add_i32 s70, s83, s60
	v_lshl_add_u64 v[214:215], s[56:57], 0, v[130:131]
	s_mov_b32 m0, s70
	ds_read_b128 v[182:185], v157 offset:16384
	ds_read_b128 v[186:189], v157 offset:17408
	ds_read_b128 v[190:193], v157 offset:18432
	ds_read_b128 v[194:197], v157 offset:19456
	ds_read_b128 v[198:201], v157 offset:20480
	ds_read_b128 v[202:205], v157 offset:21504
	ds_read_b128 v[206:209], v157 offset:22528
	ds_read_b128 v[210:213], v157 offset:23552
	global_load_lds_dwordx4 v[214:215], off
	s_add_i32 m0, s70, 0x2000
	s_add_u32 s88, s56, 0x40000
	v_lshl_add_u64 v[216:217], s[56:57], 0, v[134:135]
	s_addc_u32 s89, s57, 0
	s_add_i32 s70, s84, s60
	global_load_lds_dwordx4 v[216:217], off
	v_lshl_add_u64 v[218:219], s[88:89], 0, v[130:131]
	s_mov_b32 m0, s70
	v_lshl_add_u64 v[220:221], s[58:59], 0, v[132:133]
	global_load_lds_dwordx4 v[218:219], off
	v_lshl_add_u64 v[218:219], s[88:89], 0, v[134:135]
	s_add_i32 m0, s70, 0x2000
	s_nop 0
	global_load_lds_dwordx4 v[218:219], off
	v_lshl_add_u64 v[218:219], s[58:59], 0, v[128:129]
	s_mov_b32 m0, s63
	s_nop 0
	global_load_lds_dwordx4 v[218:219], off
	s_mov_b32 m0, s67
	s_nop 0
	global_load_lds_dwordx4 v[220:221], off
	s_waitcnt vmcnt(8) lgkmcnt(0)
	s_barrier
	v_mfma_f32_16x16x32_bf16 v[60:63], v[144:147], v[182:185], v[60:63]
	v_mfma_f32_16x16x32_bf16 v[56:59], v[158:161], v[182:185], v[56:59]
	v_mfma_f32_16x16x32_bf16 v[44:47], v[144:147], v[190:193], v[44:47]
	v_mfma_f32_16x16x32_bf16 v[40:43], v[158:161], v[190:193], v[40:43]
	v_mfma_f32_16x16x32_bf16 v[28:31], v[144:147], v[198:201], v[28:31]
	v_mfma_f32_16x16x32_bf16 v[24:27], v[158:161], v[198:201], v[24:27]
	v_mfma_f32_16x16x32_bf16 v[12:15], v[144:147], v[206:209], v[12:15]
	v_mfma_f32_16x16x32_bf16 v[8:11], v[158:161], v[206:209], v[8:11]
	v_mfma_f32_16x16x32_bf16 v[60:63], v[148:151], v[186:189], v[60:63]
	v_mfma_f32_16x16x32_bf16 v[56:59], v[162:165], v[186:189], v[56:59]
	v_mfma_f32_16x16x32_bf16 v[44:47], v[148:151], v[194:197], v[44:47]
	v_mfma_f32_16x16x32_bf16 v[40:43], v[162:165], v[194:197], v[40:43]
	v_mfma_f32_16x16x32_bf16 v[28:31], v[148:151], v[202:205], v[28:31]
	v_mfma_f32_16x16x32_bf16 v[24:27], v[162:165], v[202:205], v[24:27]
	v_mfma_f32_16x16x32_bf16 v[12:15], v[148:151], v[210:213], v[12:15]
	v_mfma_f32_16x16x32_bf16 v[8:11], v[162:165], v[210:213], v[8:11]
	v_mfma_f32_16x16x32_bf16 v[52:55], v[166:169], v[182:185], v[52:55]
	v_mfma_f32_16x16x32_bf16 v[48:51], v[174:177], v[182:185], v[48:51]
	v_mfma_f32_16x16x32_bf16 v[36:39], v[166:169], v[190:193], v[36:39]
	v_mfma_f32_16x16x32_bf16 v[32:35], v[174:177], v[190:193], v[32:35]
	v_mfma_f32_16x16x32_bf16 v[20:23], v[166:169], v[198:201], v[20:23]
	v_mfma_f32_16x16x32_bf16 v[16:19], v[174:177], v[198:201], v[16:19]
	v_mfma_f32_16x16x32_bf16 v[4:7], v[166:169], v[206:209], v[4:7]
	v_mfma_f32_16x16x32_bf16 v[0:3], v[174:177], v[206:209], v[0:3]
	v_mfma_f32_16x16x32_bf16 v[52:55], v[170:173], v[186:189], v[52:55]
	v_mfma_f32_16x16x32_bf16 v[48:51], v[178:181], v[186:189], v[48:51]
	v_mfma_f32_16x16x32_bf16 v[36:39], v[170:173], v[194:197], v[36:39]
	v_mfma_f32_16x16x32_bf16 v[32:35], v[178:181], v[194:197], v[32:35]
	v_mfma_f32_16x16x32_bf16 v[20:23], v[170:173], v[202:205], v[20:23]
	v_mfma_f32_16x16x32_bf16 v[16:19], v[178:181], v[202:205], v[16:19]
	v_mfma_f32_16x16x32_bf16 v[4:7], v[170:173], v[210:213], v[4:7]
	v_mfma_f32_16x16x32_bf16 v[0:3], v[178:181], v[210:213], v[0:3]
	s_barrier
	s_add_i32 s70, 0, 0x18000
	s_add_i32 s87, 0, 0x1c000
	v_add_u32_e32 v162, s70, v154
	v_add_u32_e32 v178, s87, v154
	ds_read_b128 v[144:147], v162
	ds_read_b128 v[148:151], v162 offset:1024
	ds_read_b128 v[158:161], v162 offset:2048
	ds_read_b128 v[162:165], v162 offset:3072
	ds_read_b128 v[166:169], v178
	ds_read_b128 v[170:173], v178 offset:1024
	ds_read_b128 v[174:177], v178 offset:2048
	ds_read_b128 v[178:181], v178 offset:3072
	s_add_u32 s58, s58, 0x40000
	s_addc_u32 s59, s59, 0
	s_mov_b32 m0, s68
	v_lshl_add_u64 v[222:223], s[58:59], 0, v[128:129]
	ds_read_b128 v[182:185], v157 offset:32768
	ds_read_b128 v[186:189], v157 offset:33792
	ds_read_b128 v[190:193], v157 offset:34816
	ds_read_b128 v[194:197], v157 offset:35840
	ds_read_b128 v[198:201], v157 offset:36864
	ds_read_b128 v[202:205], v157 offset:37888
	ds_read_b128 v[206:209], v157 offset:38912
	ds_read_b128 v[210:213], v157 offset:39936
	global_load_lds_dwordx4 v[222:223], off
	v_lshl_add_u64 v[222:223], s[58:59], 0, v[132:133]
	s_mov_b32 m0, s69
	s_nop 0
	global_load_lds_dwordx4 v[222:223], off
	s_waitcnt vmcnt(8) lgkmcnt(0)
	s_barrier
	v_mfma_f32_16x16x32_bf16 v[124:127], v[144:147], v[182:185], v[124:127]
	v_mfma_f32_16x16x32_bf16 v[120:123], v[158:161], v[182:185], v[120:123]
	v_mfma_f32_16x16x32_bf16 v[108:111], v[144:147], v[190:193], v[108:111]
	v_mfma_f32_16x16x32_bf16 v[104:107], v[158:161], v[190:193], v[104:107]
	v_mfma_f32_16x16x32_bf16 v[92:95], v[144:147], v[198:201], v[92:95]
	v_mfma_f32_16x16x32_bf16 v[88:91], v[158:161], v[198:201], v[88:91]
	v_mfma_f32_16x16x32_bf16 v[76:79], v[144:147], v[206:209], v[76:79]
	v_mfma_f32_16x16x32_bf16 v[72:75], v[158:161], v[206:209], v[72:75]
	v_mfma_f32_16x16x32_bf16 v[124:127], v[148:151], v[186:189], v[124:127]
	v_mfma_f32_16x16x32_bf16 v[120:123], v[162:165], v[186:189], v[120:123]
	v_mfma_f32_16x16x32_bf16 v[108:111], v[148:151], v[194:197], v[108:111]
	v_mfma_f32_16x16x32_bf16 v[104:107], v[162:165], v[194:197], v[104:107]
	v_mfma_f32_16x16x32_bf16 v[92:95], v[148:151], v[202:205], v[92:95]
	v_mfma_f32_16x16x32_bf16 v[88:91], v[162:165], v[202:205], v[88:91]
	v_mfma_f32_16x16x32_bf16 v[76:79], v[148:151], v[210:213], v[76:79]
	v_mfma_f32_16x16x32_bf16 v[72:75], v[162:165], v[210:213], v[72:75]
	v_mfma_f32_16x16x32_bf16 v[116:119], v[166:169], v[182:185], v[116:119]
	v_mfma_f32_16x16x32_bf16 v[112:115], v[174:177], v[182:185], v[112:115]
	v_mfma_f32_16x16x32_bf16 v[100:103], v[166:169], v[190:193], v[100:103]
	v_mfma_f32_16x16x32_bf16 v[96:99], v[174:177], v[190:193], v[96:99]
	v_mfma_f32_16x16x32_bf16 v[84:87], v[166:169], v[198:201], v[84:87]
	v_mfma_f32_16x16x32_bf16 v[80:83], v[174:177], v[198:201], v[80:83]
	v_mfma_f32_16x16x32_bf16 v[68:71], v[166:169], v[206:209], v[68:71]
	v_mfma_f32_16x16x32_bf16 v[64:67], v[174:177], v[206:209], v[64:67]
	v_mfma_f32_16x16x32_bf16 v[116:119], v[170:173], v[186:189], v[116:119]
	v_mfma_f32_16x16x32_bf16 v[112:115], v[178:181], v[186:189], v[112:115]
	v_mfma_f32_16x16x32_bf16 v[100:103], v[170:173], v[194:197], v[100:103]
	v_mfma_f32_16x16x32_bf16 v[96:99], v[178:181], v[194:197], v[96:99]
	v_mfma_f32_16x16x32_bf16 v[84:87], v[170:173], v[202:205], v[84:87]
	v_mfma_f32_16x16x32_bf16 v[80:83], v[178:181], v[202:205], v[80:83]
	v_mfma_f32_16x16x32_bf16 v[68:71], v[170:173], v[210:213], v[68:71]
	v_mfma_f32_16x16x32_bf16 v[64:67], v[178:181], v[210:213], v[64:67]
	s_barrier
	s_add_i32 s58, s70, s60
	v_lshl_add_u64 v[214:215], v[214:215], 0, s[18:19]
	s_mov_b32 m0, s58
	ds_read_b128 v[182:185], v157 offset:49152
	ds_read_b128 v[186:189], v157 offset:50176
	ds_read_b128 v[190:193], v157 offset:51200
	ds_read_b128 v[194:197], v157 offset:52224
	ds_read_b128 v[198:201], v157 offset:53248
	ds_read_b128 v[202:205], v157 offset:54272
	ds_read_b128 v[206:209], v157 offset:55296
	ds_read_b128 v[210:213], v157 offset:56320
	global_load_lds_dwordx4 v[214:215], off
	s_add_i32 m0, s58, 0x2000
	s_add_u32 s56, s56, 0x40080
	v_lshl_add_u64 v[214:215], v[216:217], 0, s[18:19]
	s_addc_u32 s57, s57, 0
	s_add_i32 s58, s87, s60
	global_load_lds_dwordx4 v[214:215], off
	v_lshl_add_u64 v[214:215], s[56:57], 0, v[130:131]
	s_mov_b32 m0, s58
	s_nop 0
	global_load_lds_dwordx4 v[214:215], off
	v_lshl_add_u64 v[214:215], s[56:57], 0, v[134:135]
	s_add_i32 m0, s58, 0x2000
	s_nop 0
	global_load_lds_dwordx4 v[214:215], off
	v_lshl_add_u64 v[214:215], v[218:219], 0, s[18:19]
	s_mov_b32 m0, s80
	s_nop 0
	global_load_lds_dwordx4 v[214:215], off
	v_lshl_add_u64 v[214:215], v[220:221], 0, s[18:19]
	s_mov_b32 m0, s81
	s_nop 0
	global_load_lds_dwordx4 v[214:215], off
	s_waitcnt vmcnt(8) lgkmcnt(0)
	s_barrier
	v_mfma_f32_16x16x32_bf16 v[60:63], v[144:147], v[182:185], v[60:63]
	v_mfma_f32_16x16x32_bf16 v[56:59], v[158:161], v[182:185], v[56:59]
	v_mfma_f32_16x16x32_bf16 v[44:47], v[144:147], v[190:193], v[44:47]
	v_mfma_f32_16x16x32_bf16 v[40:43], v[158:161], v[190:193], v[40:43]
	v_mfma_f32_16x16x32_bf16 v[28:31], v[144:147], v[198:201], v[28:31]
	v_mfma_f32_16x16x32_bf16 v[24:27], v[158:161], v[198:201], v[24:27]
	v_mfma_f32_16x16x32_bf16 v[12:15], v[144:147], v[206:209], v[12:15]
	v_mfma_f32_16x16x32_bf16 v[8:11], v[158:161], v[206:209], v[8:11]
	v_mfma_f32_16x16x32_bf16 v[60:63], v[148:151], v[186:189], v[60:63]
	v_mfma_f32_16x16x32_bf16 v[56:59], v[162:165], v[186:189], v[56:59]
	v_mfma_f32_16x16x32_bf16 v[44:47], v[148:151], v[194:197], v[44:47]
	v_mfma_f32_16x16x32_bf16 v[40:43], v[162:165], v[194:197], v[40:43]
	v_mfma_f32_16x16x32_bf16 v[28:31], v[148:151], v[202:205], v[28:31]
	v_mfma_f32_16x16x32_bf16 v[24:27], v[162:165], v[202:205], v[24:27]
	v_mfma_f32_16x16x32_bf16 v[12:15], v[148:151], v[210:213], v[12:15]
	v_mfma_f32_16x16x32_bf16 v[8:11], v[162:165], v[210:213], v[8:11]
	v_mfma_f32_16x16x32_bf16 v[52:55], v[166:169], v[182:185], v[52:55]
	v_mfma_f32_16x16x32_bf16 v[48:51], v[174:177], v[182:185], v[48:51]
	v_mfma_f32_16x16x32_bf16 v[36:39], v[166:169], v[190:193], v[36:39]
	v_mfma_f32_16x16x32_bf16 v[32:35], v[174:177], v[190:193], v[32:35]
	v_mfma_f32_16x16x32_bf16 v[20:23], v[166:169], v[198:201], v[20:23]
	v_mfma_f32_16x16x32_bf16 v[16:19], v[174:177], v[198:201], v[16:19]
	v_mfma_f32_16x16x32_bf16 v[4:7], v[166:169], v[206:209], v[4:7]
	v_mfma_f32_16x16x32_bf16 v[0:3], v[174:177], v[206:209], v[0:3]
	v_mfma_f32_16x16x32_bf16 v[52:55], v[170:173], v[186:189], v[52:55]
	v_mfma_f32_16x16x32_bf16 v[48:51], v[178:181], v[186:189], v[48:51]
	v_mfma_f32_16x16x32_bf16 v[36:39], v[170:173], v[194:197], v[36:39]
	v_mfma_f32_16x16x32_bf16 v[32:35], v[178:181], v[194:197], v[32:35]
	v_mfma_f32_16x16x32_bf16 v[20:23], v[170:173], v[202:205], v[20:23]
	v_mfma_f32_16x16x32_bf16 v[16:19], v[178:181], v[202:205], v[16:19]
	v_mfma_f32_16x16x32_bf16 v[4:7], v[170:173], v[210:213], v[4:7]
	v_mfma_f32_16x16x32_bf16 v[0:3], v[178:181], v[210:213], v[0:3]
	s_barrier
	s_add_i32 s86, s86, 2
	s_add_u32 s47, s47, 0x100
	s_addc_u32 s53, s53, 0
	s_add_u32 s54, s54, 0x100
	s_addc_u32 s55, s55, 0
	s_cmp_gt_u32 s86, 13
	s_cbranch_scc0 .LBB0_201
	s_and_b64 vcc, exec, s[42:43]
	s_cbranch_vccz .LBB0_204
	s_barrier

.LBB0_733:
	ds_read_b128 v[144:147], v151
	ds_read_b128 v[154:157], v151 offset:1024
	ds_read_b128 v[158:161], v151 offset:2048
	ds_read_b128 v[162:165], v151 offset:3072
	ds_read_b128 v[166:169], v152
	ds_read_b128 v[170:173], v152 offset:1024
	ds_read_b128 v[174:177], v152 offset:2048
	ds_read_b128 v[178:181], v152 offset:3072
	s_add_u32 s22, s46, 0xfffc0080
	s_addc_u32 s23, s47, -1
	s_cmp_eq_u32 s71, 12
	s_cselect_b32 s51, s26, s23
	s_cselect_b32 s50, s27, s22
	s_cselect_b32 s49, s39, s69
	s_cselect_b32 s48, s41, s68
	v_lshl_add_u64 v[214:215], s[46:47], 0, v[138:139]
	s_add_i32 m0, s13, 0xc000
	ds_read_b128 v[182:185], v153
	ds_read_b128 v[186:189], v153 offset:1024
	ds_read_b128 v[190:193], v153 offset:2048
	ds_read_b128 v[194:197], v153 offset:3072
	ds_read_b128 v[198:201], v153 offset:4096
	ds_read_b128 v[202:205], v153 offset:5120
	ds_read_b128 v[206:209], v153 offset:6144
	ds_read_b128 v[210:213], v153 offset:7168
	global_load_lds_dwordx4 v[214:215], off
	v_lshl_add_u64 v[214:215], s[46:47], 0, v[136:137]
	s_add_i32 m0, s13, 0xe000
	s_nop 0
	global_load_lds_dwordx4 v[214:215], off
	s_waitcnt vmcnt(8) lgkmcnt(0)
	s_barrier
	v_mfma_f32_16x16x32_bf16 v[124:127], v[144:147], v[182:185], v[124:127]
	v_mfma_f32_16x16x32_bf16 v[120:123], v[158:161], v[182:185], v[120:123]
	v_mfma_f32_16x16x32_bf16 v[108:111], v[144:147], v[190:193], v[108:111]
	v_mfma_f32_16x16x32_bf16 v[104:107], v[158:161], v[190:193], v[104:107]
	v_mfma_f32_16x16x32_bf16 v[92:95], v[144:147], v[198:201], v[92:95]
	v_mfma_f32_16x16x32_bf16 v[88:91], v[158:161], v[198:201], v[88:91]
	v_mfma_f32_16x16x32_bf16 v[76:79], v[144:147], v[206:209], v[76:79]
	v_mfma_f32_16x16x32_bf16 v[72:75], v[158:161], v[206:209], v[72:75]
	v_mfma_f32_16x16x32_bf16 v[124:127], v[154:157], v[186:189], v[124:127]
	v_mfma_f32_16x16x32_bf16 v[120:123], v[162:165], v[186:189], v[120:123]
	v_mfma_f32_16x16x32_bf16 v[108:111], v[154:157], v[194:197], v[108:111]
	v_mfma_f32_16x16x32_bf16 v[104:107], v[162:165], v[194:197], v[104:107]
	v_mfma_f32_16x16x32_bf16 v[92:95], v[154:157], v[202:205], v[92:95]
	v_mfma_f32_16x16x32_bf16 v[88:91], v[162:165], v[202:205], v[88:91]
	v_mfma_f32_16x16x32_bf16 v[76:79], v[154:157], v[210:213], v[76:79]
	v_mfma_f32_16x16x32_bf16 v[72:75], v[162:165], v[210:213], v[72:75]
	v_mfma_f32_16x16x32_bf16 v[116:119], v[166:169], v[182:185], v[116:119]
	v_mfma_f32_16x16x32_bf16 v[112:115], v[174:177], v[182:185], v[112:115]
	v_mfma_f32_16x16x32_bf16 v[100:103], v[166:169], v[190:193], v[100:103]
	v_mfma_f32_16x16x32_bf16 v[96:99], v[174:177], v[190:193], v[96:99]
	v_mfma_f32_16x16x32_bf16 v[84:87], v[166:169], v[198:201], v[84:87]
	v_mfma_f32_16x16x32_bf16 v[80:83], v[174:177], v[198:201], v[80:83]
	v_mfma_f32_16x16x32_bf16 v[68:71], v[166:169], v[206:209], v[68:71]
	v_mfma_f32_16x16x32_bf16 v[64:67], v[174:177], v[206:209], v[64:67]
	v_mfma_f32_16x16x32_bf16 v[116:119], v[170:173], v[186:189], v[116:119]
	v_mfma_f32_16x16x32_bf16 v[112:115], v[178:181], v[186:189], v[112:115]
	v_mfma_f32_16x16x32_bf16 v[100:103], v[170:173], v[194:197], v[100:103]
	v_mfma_f32_16x16x32_bf16 v[96:99], v[178:181], v[194:197], v[96:99]
	v_mfma_f32_16x16x32_bf16 v[84:87], v[170:173], v[202:205], v[84:87]
	v_mfma_f32_16x16x32_bf16 v[80:83], v[178:181], v[202:205], v[80:83]
	v_mfma_f32_16x16x32_bf16 v[68:71], v[170:173], v[210:213], v[68:71]
	v_mfma_f32_16x16x32_bf16 v[64:67], v[178:181], v[210:213], v[64:67]
	s_barrier
	s_add_i32 s22, s65, s56
	v_lshl_add_u64 v[214:215], s[48:49], 0, v[130:131]
	s_mov_b32 m0, s22
	ds_read_b128 v[182:185], v153 offset:16384
	ds_read_b128 v[186:189], v153 offset:17408
	ds_read_b128 v[190:193], v153 offset:18432
	ds_read_b128 v[194:197], v153 offset:19456
	ds_read_b128 v[198:201], v153 offset:20480
	ds_read_b128 v[202:205], v153 offset:21504
	ds_read_b128 v[206:209], v153 offset:22528
	ds_read_b128 v[210:213], v153 offset:23552
	global_load_lds_dwordx4 v[214:215], off
	s_add_i32 m0, s22, 0x2000
	s_add_u32 s80, s48, 0x40000
	v_lshl_add_u64 v[216:217], s[48:49], 0, v[134:135]
	s_addc_u32 s81, s49, 0
	s_add_i32 s22, s66, s56
	global_load_lds_dwordx4 v[216:217], off
	v_lshl_add_u64 v[218:219], s[80:81], 0, v[130:131]
	s_mov_b32 m0, s22
	v_lshl_add_u64 v[220:221], s[50:51], 0, v[132:133]
	global_load_lds_dwordx4 v[218:219], off
	v_lshl_add_u64 v[218:219], s[80:81], 0, v[134:135]
	s_add_i32 m0, s22, 0x2000
	s_nop 0
	global_load_lds_dwordx4 v[218:219], off
	v_lshl_add_u64 v[218:219], s[50:51], 0, v[128:129]
	s_mov_b32 m0, s13
	s_nop 0
	global_load_lds_dwordx4 v[218:219], off
	s_mov_b32 m0, s57
	s_nop 0
	global_load_lds_dwordx4 v[220:221], off
	s_waitcnt vmcnt(8) lgkmcnt(0)
	s_barrier
	v_mfma_f32_16x16x32_bf16 v[60:63], v[144:147], v[182:185], v[60:63]
	v_mfma_f32_16x16x32_bf16 v[56:59], v[158:161], v[182:185], v[56:59]
	v_mfma_f32_16x16x32_bf16 v[44:47], v[144:147], v[190:193], v[44:47]
	v_mfma_f32_16x16x32_bf16 v[40:43], v[158:161], v[190:193], v[40:43]
	v_mfma_f32_16x16x32_bf16 v[28:31], v[144:147], v[198:201], v[28:31]
	v_mfma_f32_16x16x32_bf16 v[24:27], v[158:161], v[198:201], v[24:27]
	v_mfma_f32_16x16x32_bf16 v[12:15], v[144:147], v[206:209], v[12:15]
	v_mfma_f32_16x16x32_bf16 v[8:11], v[158:161], v[206:209], v[8:11]
	v_mfma_f32_16x16x32_bf16 v[60:63], v[154:157], v[186:189], v[60:63]
	v_mfma_f32_16x16x32_bf16 v[56:59], v[162:165], v[186:189], v[56:59]
	v_mfma_f32_16x16x32_bf16 v[44:47], v[154:157], v[194:197], v[44:47]
	v_mfma_f32_16x16x32_bf16 v[40:43], v[162:165], v[194:197], v[40:43]
	v_mfma_f32_16x16x32_bf16 v[28:31], v[154:157], v[202:205], v[28:31]
	v_mfma_f32_16x16x32_bf16 v[24:27], v[162:165], v[202:205], v[24:27]
	v_mfma_f32_16x16x32_bf16 v[12:15], v[154:157], v[210:213], v[12:15]
	v_mfma_f32_16x16x32_bf16 v[8:11], v[162:165], v[210:213], v[8:11]
	v_mfma_f32_16x16x32_bf16 v[52:55], v[166:169], v[182:185], v[52:55]
	v_mfma_f32_16x16x32_bf16 v[48:51], v[174:177], v[182:185], v[48:51]
	v_mfma_f32_16x16x32_bf16 v[36:39], v[166:169], v[190:193], v[36:39]
	v_mfma_f32_16x16x32_bf16 v[32:35], v[174:177], v[190:193], v[32:35]
	v_mfma_f32_16x16x32_bf16 v[20:23], v[166:169], v[198:201], v[20:23]
	v_mfma_f32_16x16x32_bf16 v[16:19], v[174:177], v[198:201], v[16:19]
	v_mfma_f32_16x16x32_bf16 v[4:7], v[166:169], v[206:209], v[4:7]
	v_mfma_f32_16x16x32_bf16 v[0:3], v[174:177], v[206:209], v[0:3]
	v_mfma_f32_16x16x32_bf16 v[52:55], v[170:173], v[186:189], v[52:55]
	v_mfma_f32_16x16x32_bf16 v[48:51], v[178:181], v[186:189], v[48:51]
	v_mfma_f32_16x16x32_bf16 v[36:39], v[170:173], v[194:197], v[36:39]
	v_mfma_f32_16x16x32_bf16 v[32:35], v[178:181], v[194:197], v[32:35]
	v_mfma_f32_16x16x32_bf16 v[20:23], v[170:173], v[202:205], v[20:23]
	v_mfma_f32_16x16x32_bf16 v[16:19], v[178:181], v[202:205], v[16:19]
	v_mfma_f32_16x16x32_bf16 v[4:7], v[170:173], v[210:213], v[4:7]
	v_mfma_f32_16x16x32_bf16 v[0:3], v[178:181], v[210:213], v[0:3]
	s_barrier
	s_add_i32 s22, 0, 0x18000
	s_add_i32 s23, 0, 0x1c000
	v_add_u32_e32 v162, s22, v150
	v_add_u32_e32 v178, s23, v150
	ds_read_b128 v[144:147], v162
	ds_read_b128 v[154:157], v162 offset:1024
	ds_read_b128 v[158:161], v162 offset:2048
	ds_read_b128 v[162:165], v162 offset:3072
	ds_read_b128 v[166:169], v178
	ds_read_b128 v[170:173], v178 offset:1024
	ds_read_b128 v[174:177], v178 offset:2048
	ds_read_b128 v[178:181], v178 offset:3072
	s_add_u32 s50, s50, 0x40000
	s_addc_u32 s51, s51, 0
	s_mov_b32 m0, s58
	v_lshl_add_u64 v[222:223], s[50:51], 0, v[128:129]
	ds_read_b128 v[182:185], v153 offset:32768
	ds_read_b128 v[186:189], v153 offset:33792
	ds_read_b128 v[190:193], v153 offset:34816
	ds_read_b128 v[194:197], v153 offset:35840
	ds_read_b128 v[198:201], v153 offset:36864
	ds_read_b128 v[202:205], v153 offset:37888
	ds_read_b128 v[206:209], v153 offset:38912
	ds_read_b128 v[210:213], v153 offset:39936
	global_load_lds_dwordx4 v[222:223], off
	v_lshl_add_u64 v[222:223], s[50:51], 0, v[132:133]
	s_mov_b32 m0, s59
	s_nop 0
	global_load_lds_dwordx4 v[222:223], off
	s_waitcnt vmcnt(8) lgkmcnt(0)
	s_barrier
	v_mfma_f32_16x16x32_bf16 v[124:127], v[144:147], v[182:185], v[124:127]
	v_mfma_f32_16x16x32_bf16 v[120:123], v[158:161], v[182:185], v[120:123]
	v_mfma_f32_16x16x32_bf16 v[108:111], v[144:147], v[190:193], v[108:111]
	v_mfma_f32_16x16x32_bf16 v[104:107], v[158:161], v[190:193], v[104:107]
	v_mfma_f32_16x16x32_bf16 v[92:95], v[144:147], v[198:201], v[92:95]
	v_mfma_f32_16x16x32_bf16 v[88:91], v[158:161], v[198:201], v[88:91]
	v_mfma_f32_16x16x32_bf16 v[76:79], v[144:147], v[206:209], v[76:79]
	v_mfma_f32_16x16x32_bf16 v[72:75], v[158:161], v[206:209], v[72:75]
	v_mfma_f32_16x16x32_bf16 v[124:127], v[154:157], v[186:189], v[124:127]
	v_mfma_f32_16x16x32_bf16 v[120:123], v[162:165], v[186:189], v[120:123]
	v_mfma_f32_16x16x32_bf16 v[108:111], v[154:157], v[194:197], v[108:111]
	v_mfma_f32_16x16x32_bf16 v[104:107], v[162:165], v[194:197], v[104:107]
	v_mfma_f32_16x16x32_bf16 v[92:95], v[154:157], v[202:205], v[92:95]
	v_mfma_f32_16x16x32_bf16 v[88:91], v[162:165], v[202:205], v[88:91]
	v_mfma_f32_16x16x32_bf16 v[76:79], v[154:157], v[210:213], v[76:79]
	v_mfma_f32_16x16x32_bf16 v[72:75], v[162:165], v[210:213], v[72:75]
	v_mfma_f32_16x16x32_bf16 v[116:119], v[166:169], v[182:185], v[116:119]
	v_mfma_f32_16x16x32_bf16 v[112:115], v[174:177], v[182:185], v[112:115]
	v_mfma_f32_16x16x32_bf16 v[100:103], v[166:169], v[190:193], v[100:103]
	v_mfma_f32_16x16x32_bf16 v[96:99], v[174:177], v[190:193], v[96:99]
	v_mfma_f32_16x16x32_bf16 v[84:87], v[166:169], v[198:201], v[84:87]
	v_mfma_f32_16x16x32_bf16 v[80:83], v[174:177], v[198:201], v[80:83]
	v_mfma_f32_16x16x32_bf16 v[68:71], v[166:169], v[206:209], v[68:71]
	v_mfma_f32_16x16x32_bf16 v[64:67], v[174:177], v[206:209], v[64:67]
	v_mfma_f32_16x16x32_bf16 v[116:119], v[170:173], v[186:189], v[116:119]
	v_mfma_f32_16x16x32_bf16 v[112:115], v[178:181], v[186:189], v[112:115]
	v_mfma_f32_16x16x32_bf16 v[100:103], v[170:173], v[194:197], v[100:103]
	v_mfma_f32_16x16x32_bf16 v[96:99], v[178:181], v[194:197], v[96:99]
	v_mfma_f32_16x16x32_bf16 v[84:87], v[170:173], v[202:205], v[84:87]
	v_mfma_f32_16x16x32_bf16 v[80:83], v[178:181], v[202:205], v[80:83]
	v_mfma_f32_16x16x32_bf16 v[68:71], v[170:173], v[210:213], v[68:71]
	v_mfma_f32_16x16x32_bf16 v[64:67], v[178:181], v[210:213], v[64:67]
	s_barrier
	s_add_i32 s22, s22, s56
	v_lshl_add_u64 v[214:215], v[214:215], 0, s[34:35]
	s_mov_b32 m0, s22
	ds_read_b128 v[182:185], v153 offset:49152
	ds_read_b128 v[186:189], v153 offset:50176
	ds_read_b128 v[190:193], v153 offset:51200
	ds_read_b128 v[194:197], v153 offset:52224
	ds_read_b128 v[198:201], v153 offset:53248
	ds_read_b128 v[202:205], v153 offset:54272
	ds_read_b128 v[206:209], v153 offset:55296
	ds_read_b128 v[210:213], v153 offset:56320
	global_load_lds_dwordx4 v[214:215], off
	s_add_i32 m0, s22, 0x2000
	s_add_u32 s48, s48, 0x40080
	v_lshl_add_u64 v[214:215], v[216:217], 0, s[34:35]
	s_addc_u32 s49, s49, 0
	s_add_i32 s22, s23, s56
	global_load_lds_dwordx4 v[214:215], off
	v_lshl_add_u64 v[214:215], s[48:49], 0, v[130:131]
	s_mov_b32 m0, s22
	s_nop 0
	global_load_lds_dwordx4 v[214:215], off
	v_lshl_add_u64 v[214:215], s[48:49], 0, v[134:135]
	s_add_i32 m0, s22, 0x2000
	s_nop 0
	global_load_lds_dwordx4 v[214:215], off
	v_lshl_add_u64 v[214:215], v[218:219], 0, s[34:35]
	s_mov_b32 m0, s63
	s_nop 0
	global_load_lds_dwordx4 v[214:215], off
	v_lshl_add_u64 v[214:215], v[220:221], 0, s[34:35]
	s_mov_b32 m0, s64
	s_nop 0
	global_load_lds_dwordx4 v[214:215], off
	s_waitcnt vmcnt(8) lgkmcnt(0)
	s_barrier
	v_mfma_f32_16x16x32_bf16 v[60:63], v[144:147], v[182:185], v[60:63]
	v_mfma_f32_16x16x32_bf16 v[56:59], v[158:161], v[182:185], v[56:59]
	v_mfma_f32_16x16x32_bf16 v[44:47], v[144:147], v[190:193], v[44:47]
	v_mfma_f32_16x16x32_bf16 v[40:43], v[158:161], v[190:193], v[40:43]
	v_mfma_f32_16x16x32_bf16 v[28:31], v[144:147], v[198:201], v[28:31]
	v_mfma_f32_16x16x32_bf16 v[24:27], v[158:161], v[198:201], v[24:27]
	v_mfma_f32_16x16x32_bf16 v[12:15], v[144:147], v[206:209], v[12:15]
	v_mfma_f32_16x16x32_bf16 v[8:11], v[158:161], v[206:209], v[8:11]
	v_mfma_f32_16x16x32_bf16 v[60:63], v[154:157], v[186:189], v[60:63]
	v_mfma_f32_16x16x32_bf16 v[56:59], v[162:165], v[186:189], v[56:59]
	v_mfma_f32_16x16x32_bf16 v[44:47], v[154:157], v[194:197], v[44:47]
	v_mfma_f32_16x16x32_bf16 v[40:43], v[162:165], v[194:197], v[40:43]
	v_mfma_f32_16x16x32_bf16 v[28:31], v[154:157], v[202:205], v[28:31]
	v_mfma_f32_16x16x32_bf16 v[24:27], v[162:165], v[202:205], v[24:27]
	v_mfma_f32_16x16x32_bf16 v[12:15], v[154:157], v[210:213], v[12:15]
	v_mfma_f32_16x16x32_bf16 v[8:11], v[162:165], v[210:213], v[8:11]
	v_mfma_f32_16x16x32_bf16 v[52:55], v[166:169], v[182:185], v[52:55]
	v_mfma_f32_16x16x32_bf16 v[48:51], v[174:177], v[182:185], v[48:51]
	v_mfma_f32_16x16x32_bf16 v[36:39], v[166:169], v[190:193], v[36:39]
	v_mfma_f32_16x16x32_bf16 v[32:35], v[174:177], v[190:193], v[32:35]
	v_mfma_f32_16x16x32_bf16 v[20:23], v[166:169], v[198:201], v[20:23]
	v_mfma_f32_16x16x32_bf16 v[16:19], v[174:177], v[198:201], v[16:19]
	v_mfma_f32_16x16x32_bf16 v[4:7], v[166:169], v[206:209], v[4:7]
	v_mfma_f32_16x16x32_bf16 v[0:3], v[174:177], v[206:209], v[0:3]
	v_mfma_f32_16x16x32_bf16 v[52:55], v[170:173], v[186:189], v[52:55]
	v_mfma_f32_16x16x32_bf16 v[48:51], v[178:181], v[186:189], v[48:51]
	v_mfma_f32_16x16x32_bf16 v[36:39], v[170:173], v[194:197], v[36:39]
	v_mfma_f32_16x16x32_bf16 v[32:35], v[178:181], v[194:197], v[32:35]
	v_mfma_f32_16x16x32_bf16 v[20:23], v[170:173], v[202:205], v[20:23]
	v_mfma_f32_16x16x32_bf16 v[16:19], v[178:181], v[202:205], v[16:19]
	v_mfma_f32_16x16x32_bf16 v[4:7], v[170:173], v[210:213], v[4:7]
	v_mfma_f32_16x16x32_bf16 v[0:3], v[178:181], v[210:213], v[0:3]
	s_barrier
	s_add_i32 s71, s71, 2
	s_add_u32 s68, s68, 0x100
	s_addc_u32 s69, s69, 0
	s_add_u32 s46, s46, 0x100
	s_addc_u32 s47, s47, 0
	s_cmp_gt_u32 s71, 13
	s_cbranch_scc0 .LBB0_733
	s_and_b64 vcc, exec, s[36:37]
	s_cbranch_vccz .LBB0_736
	s_barrier

.LBB0_849:
	ds_read_b128 v[146:149], v227
	ds_read_b128 v[150:153], v227 offset:1024
	ds_read_b128 v[154:157], v227 offset:2048
	ds_read_b128 v[158:161], v227 offset:3072
	ds_read_b128 v[162:165], v228
	ds_read_b128 v[166:169], v228 offset:1024
	ds_read_b128 v[170:173], v228 offset:2048
	ds_read_b128 v[174:177], v228 offset:3072
	s_add_u32 s22, s12, 0xfffc2080
	s_addc_u32 s23, s13, -1
	s_cmp_eq_u32 vcc_hi, 12
	s_cselect_b32 s65, s59, s23
	s_cselect_b32 s64, s58, s22
	s_cselect_b32 s63, s27, vcc_lo
	s_cselect_b32 s62, s57, s71
	v_lshl_add_u64 v[210:211], s[12:13], 0, v[138:139]
	s_add_i32 m0, s69, 0xc000
	ds_read_b128 v[178:181], v229
	ds_read_b128 v[182:185], v229 offset:1024
	ds_read_b128 v[186:189], v229 offset:2048
	ds_read_b128 v[190:193], v229 offset:3072
	ds_read_b128 v[194:197], v229 offset:4096
	ds_read_b128 v[198:201], v229 offset:5120
	ds_read_b128 v[202:205], v229 offset:6144
	ds_read_b128 v[206:209], v229 offset:7168
	global_load_lds_dwordx4 v[210:211], off
	v_lshl_add_u64 v[210:211], s[12:13], 0, v[136:137]
	s_add_i32 m0, s69, 0xe000
	s_nop 0
	global_load_lds_dwordx4 v[210:211], off
	s_waitcnt vmcnt(8) lgkmcnt(0)
	s_barrier
	v_mfma_f32_16x16x32_bf16 v[124:127], v[146:149], v[178:181], v[124:127]
	v_mfma_f32_16x16x32_bf16 v[120:123], v[154:157], v[178:181], v[120:123]
	v_mfma_f32_16x16x32_bf16 v[116:119], v[146:149], v[186:189], v[116:119]
	v_mfma_f32_16x16x32_bf16 v[108:111], v[154:157], v[186:189], v[108:111]
	v_mfma_f32_16x16x32_bf16 v[100:103], v[146:149], v[194:197], v[100:103]
	v_mfma_f32_16x16x32_bf16 v[96:99], v[154:157], v[194:197], v[96:99]
	v_mfma_f32_16x16x32_bf16 v[84:87], v[146:149], v[202:205], v[84:87]
	v_mfma_f32_16x16x32_bf16 v[76:79], v[154:157], v[202:205], v[76:79]
	v_mfma_f32_16x16x32_bf16 v[124:127], v[150:153], v[182:185], v[124:127]
	v_mfma_f32_16x16x32_bf16 v[120:123], v[158:161], v[182:185], v[120:123]
	v_mfma_f32_16x16x32_bf16 v[116:119], v[150:153], v[190:193], v[116:119]
	v_mfma_f32_16x16x32_bf16 v[108:111], v[158:161], v[190:193], v[108:111]
	v_mfma_f32_16x16x32_bf16 v[100:103], v[150:153], v[198:201], v[100:103]
	v_mfma_f32_16x16x32_bf16 v[96:99], v[158:161], v[198:201], v[96:99]
	v_mfma_f32_16x16x32_bf16 v[84:87], v[150:153], v[206:209], v[84:87]
	v_mfma_f32_16x16x32_bf16 v[76:79], v[158:161], v[206:209], v[76:79]
	v_mfma_f32_16x16x32_bf16 v[112:115], v[162:165], v[178:181], v[112:115]
	v_mfma_f32_16x16x32_bf16 v[104:107], v[170:173], v[178:181], v[104:107]
	v_mfma_f32_16x16x32_bf16 v[92:95], v[162:165], v[186:189], v[92:95]
	v_mfma_f32_16x16x32_bf16 v[88:91], v[170:173], v[186:189], v[88:91]
	v_mfma_f32_16x16x32_bf16 v[80:83], v[162:165], v[194:197], v[80:83]
	v_mfma_f32_16x16x32_bf16 v[72:75], v[170:173], v[194:197], v[72:75]
	v_mfma_f32_16x16x32_bf16 v[68:71], v[162:165], v[202:205], v[68:71]
	v_mfma_f32_16x16x32_bf16 v[64:67], v[170:173], v[202:205], v[64:67]
	v_mfma_f32_16x16x32_bf16 v[112:115], v[166:169], v[182:185], v[112:115]
	v_mfma_f32_16x16x32_bf16 v[104:107], v[174:177], v[182:185], v[104:107]
	v_mfma_f32_16x16x32_bf16 v[92:95], v[166:169], v[190:193], v[92:95]
	v_mfma_f32_16x16x32_bf16 v[88:91], v[174:177], v[190:193], v[88:91]
	v_mfma_f32_16x16x32_bf16 v[80:83], v[166:169], v[198:201], v[80:83]
	v_mfma_f32_16x16x32_bf16 v[72:75], v[174:177], v[198:201], v[72:75]
	v_mfma_f32_16x16x32_bf16 v[68:71], v[166:169], v[206:209], v[68:71]
	v_mfma_f32_16x16x32_bf16 v[64:67], v[174:177], v[206:209], v[64:67]
	s_barrier
	s_add_i32 s22, s91, s53
	v_lshl_add_u64 v[210:211], s[62:63], 0, v[130:131]
	s_mov_b32 m0, s22
	ds_read_b128 v[178:181], v229 offset:16384
	ds_read_b128 v[182:185], v229 offset:17408
	ds_read_b128 v[186:189], v229 offset:18432
	ds_read_b128 v[190:193], v229 offset:19456
	ds_read_b128 v[194:197], v229 offset:20480
	ds_read_b128 v[198:201], v229 offset:21504
	ds_read_b128 v[202:205], v229 offset:22528
	ds_read_b128 v[206:209], v229 offset:23552
	global_load_lds_dwordx4 v[210:211], off
	s_add_i32 m0, s22, 0x2000
	s_add_u32 s22, s62, 0x40000
	v_lshl_add_u64 v[212:213], s[62:63], 0, v[134:135]
	s_addc_u32 s23, s63, 0
	s_add_i32 s70, s92, s53
	global_load_lds_dwordx4 v[212:213], off
	v_lshl_add_u64 v[214:215], s[22:23], 0, v[130:131]
	s_mov_b32 m0, s70
	v_lshl_add_u64 v[216:217], s[64:65], 0, v[132:133]
	global_load_lds_dwordx4 v[214:215], off
	v_lshl_add_u64 v[214:215], s[22:23], 0, v[134:135]
	s_add_i32 m0, s70, 0x2000
	s_nop 0
	global_load_lds_dwordx4 v[214:215], off
	v_lshl_add_u64 v[214:215], s[64:65], 0, v[128:129]
	s_mov_b32 m0, s69
	s_nop 0
	global_load_lds_dwordx4 v[214:215], off
	s_mov_b32 m0, s82
	s_nop 0
	global_load_lds_dwordx4 v[216:217], off
	s_waitcnt vmcnt(8) lgkmcnt(0)
	s_barrier
	v_mfma_f32_16x16x32_bf16 v[60:63], v[146:149], v[178:181], v[60:63]
	v_mfma_f32_16x16x32_bf16 v[56:59], v[154:157], v[178:181], v[56:59]
	v_mfma_f32_16x16x32_bf16 v[52:55], v[146:149], v[186:189], v[52:55]
	v_mfma_f32_16x16x32_bf16 v[44:47], v[154:157], v[186:189], v[44:47]
	v_mfma_f32_16x16x32_bf16 v[36:39], v[146:149], v[194:197], v[36:39]
	v_mfma_f32_16x16x32_bf16 v[32:35], v[154:157], v[194:197], v[32:35]
	v_mfma_f32_16x16x32_bf16 v[20:23], v[146:149], v[202:205], v[20:23]
	v_mfma_f32_16x16x32_bf16 v[12:15], v[154:157], v[202:205], v[12:15]
	v_mfma_f32_16x16x32_bf16 v[60:63], v[150:153], v[182:185], v[60:63]
	v_mfma_f32_16x16x32_bf16 v[56:59], v[158:161], v[182:185], v[56:59]
	v_mfma_f32_16x16x32_bf16 v[52:55], v[150:153], v[190:193], v[52:55]
	v_mfma_f32_16x16x32_bf16 v[44:47], v[158:161], v[190:193], v[44:47]
	v_mfma_f32_16x16x32_bf16 v[36:39], v[150:153], v[198:201], v[36:39]
	v_mfma_f32_16x16x32_bf16 v[32:35], v[158:161], v[198:201], v[32:35]
	v_mfma_f32_16x16x32_bf16 v[20:23], v[150:153], v[206:209], v[20:23]
	v_mfma_f32_16x16x32_bf16 v[12:15], v[158:161], v[206:209], v[12:15]
	v_mfma_f32_16x16x32_bf16 v[48:51], v[162:165], v[178:181], v[48:51]
	v_mfma_f32_16x16x32_bf16 v[40:43], v[170:173], v[178:181], v[40:43]
	v_mfma_f32_16x16x32_bf16 v[28:31], v[162:165], v[186:189], v[28:31]
	v_mfma_f32_16x16x32_bf16 v[24:27], v[170:173], v[186:189], v[24:27]
	v_mfma_f32_16x16x32_bf16 v[16:19], v[162:165], v[194:197], v[16:19]
	v_mfma_f32_16x16x32_bf16 v[8:11], v[170:173], v[194:197], v[8:11]
	v_mfma_f32_16x16x32_bf16 v[4:7], v[162:165], v[202:205], v[4:7]
	v_mfma_f32_16x16x32_bf16 v[0:3], v[170:173], v[202:205], v[0:3]
	v_mfma_f32_16x16x32_bf16 v[48:51], v[166:169], v[182:185], v[48:51]
	v_mfma_f32_16x16x32_bf16 v[40:43], v[174:177], v[182:185], v[40:43]
	v_mfma_f32_16x16x32_bf16 v[28:31], v[166:169], v[190:193], v[28:31]
	v_mfma_f32_16x16x32_bf16 v[24:27], v[174:177], v[190:193], v[24:27]
	v_mfma_f32_16x16x32_bf16 v[16:19], v[166:169], v[198:201], v[16:19]
	v_mfma_f32_16x16x32_bf16 v[8:11], v[174:177], v[198:201], v[8:11]
	v_mfma_f32_16x16x32_bf16 v[4:7], v[166:169], v[206:209], v[4:7]
	v_mfma_f32_16x16x32_bf16 v[0:3], v[174:177], v[206:209], v[0:3]
	s_barrier
	s_add_i32 s70, 0, 0x18000
	s_add_i32 s81, 0, 0x1c000
	v_add_u32_e32 v158, s70, v226
	v_add_u32_e32 v174, s81, v226
	ds_read_b128 v[146:149], v158
	ds_read_b128 v[150:153], v158 offset:1024
	ds_read_b128 v[154:157], v158 offset:2048
	ds_read_b128 v[158:161], v158 offset:3072
	ds_read_b128 v[162:165], v174
	ds_read_b128 v[166:169], v174 offset:1024
	ds_read_b128 v[170:173], v174 offset:2048
	ds_read_b128 v[174:177], v174 offset:3072
	s_add_u32 s22, s64, 0x3e000
	s_addc_u32 s23, s65, 0
	s_mov_b32 m0, s83
	v_lshl_add_u64 v[218:219], s[22:23], 0, v[128:129]
	ds_read_b128 v[178:181], v229 offset:32768
	ds_read_b128 v[182:185], v229 offset:33792
	ds_read_b128 v[186:189], v229 offset:34816
	ds_read_b128 v[190:193], v229 offset:35840
	ds_read_b128 v[194:197], v229 offset:36864
	ds_read_b128 v[198:201], v229 offset:37888
	ds_read_b128 v[202:205], v229 offset:38912
	ds_read_b128 v[206:209], v229 offset:39936
	global_load_lds_dwordx4 v[218:219], off
	v_lshl_add_u64 v[218:219], s[22:23], 0, v[132:133]
	s_mov_b32 m0, s84
	s_nop 0
	global_load_lds_dwordx4 v[218:219], off
	s_waitcnt vmcnt(8) lgkmcnt(0)
	s_barrier
	v_mfma_f32_16x16x32_bf16 v[124:127], v[146:149], v[178:181], v[124:127]
	v_mfma_f32_16x16x32_bf16 v[120:123], v[154:157], v[178:181], v[120:123]
	v_mfma_f32_16x16x32_bf16 v[116:119], v[146:149], v[186:189], v[116:119]
	v_mfma_f32_16x16x32_bf16 v[108:111], v[154:157], v[186:189], v[108:111]
	v_mfma_f32_16x16x32_bf16 v[100:103], v[146:149], v[194:197], v[100:103]
	v_mfma_f32_16x16x32_bf16 v[96:99], v[154:157], v[194:197], v[96:99]
	v_mfma_f32_16x16x32_bf16 v[84:87], v[146:149], v[202:205], v[84:87]
	v_mfma_f32_16x16x32_bf16 v[76:79], v[154:157], v[202:205], v[76:79]
	v_mfma_f32_16x16x32_bf16 v[124:127], v[150:153], v[182:185], v[124:127]
	v_mfma_f32_16x16x32_bf16 v[120:123], v[158:161], v[182:185], v[120:123]
	v_mfma_f32_16x16x32_bf16 v[116:119], v[150:153], v[190:193], v[116:119]
	v_mfma_f32_16x16x32_bf16 v[108:111], v[158:161], v[190:193], v[108:111]
	v_mfma_f32_16x16x32_bf16 v[100:103], v[150:153], v[198:201], v[100:103]
	v_mfma_f32_16x16x32_bf16 v[96:99], v[158:161], v[198:201], v[96:99]
	v_mfma_f32_16x16x32_bf16 v[84:87], v[150:153], v[206:209], v[84:87]
	v_mfma_f32_16x16x32_bf16 v[76:79], v[158:161], v[206:209], v[76:79]
	v_mfma_f32_16x16x32_bf16 v[112:115], v[162:165], v[178:181], v[112:115]
	v_mfma_f32_16x16x32_bf16 v[104:107], v[170:173], v[178:181], v[104:107]
	v_mfma_f32_16x16x32_bf16 v[92:95], v[162:165], v[186:189], v[92:95]
	v_mfma_f32_16x16x32_bf16 v[88:91], v[170:173], v[186:189], v[88:91]
	v_mfma_f32_16x16x32_bf16 v[80:83], v[162:165], v[194:197], v[80:83]
	v_mfma_f32_16x16x32_bf16 v[72:75], v[170:173], v[194:197], v[72:75]
	v_mfma_f32_16x16x32_bf16 v[68:71], v[162:165], v[202:205], v[68:71]
	v_mfma_f32_16x16x32_bf16 v[64:67], v[170:173], v[202:205], v[64:67]
	v_mfma_f32_16x16x32_bf16 v[112:115], v[166:169], v[182:185], v[112:115]
	v_mfma_f32_16x16x32_bf16 v[104:107], v[174:177], v[182:185], v[104:107]
	v_mfma_f32_16x16x32_bf16 v[92:95], v[166:169], v[190:193], v[92:95]
	v_mfma_f32_16x16x32_bf16 v[88:91], v[174:177], v[190:193], v[88:91]
	v_mfma_f32_16x16x32_bf16 v[80:83], v[166:169], v[198:201], v[80:83]
	v_mfma_f32_16x16x32_bf16 v[72:75], v[174:177], v[198:201], v[72:75]
	v_mfma_f32_16x16x32_bf16 v[68:71], v[166:169], v[206:209], v[68:71]
	v_mfma_f32_16x16x32_bf16 v[64:67], v[174:177], v[206:209], v[64:67]
	s_barrier
	s_add_i32 s22, s70, s53
	v_lshl_add_u64 v[210:211], v[210:211], 0, s[48:49]
	s_mov_b32 m0, s22
	ds_read_b128 v[178:181], v229 offset:49152
	ds_read_b128 v[182:185], v229 offset:50176
	ds_read_b128 v[186:189], v229 offset:51200
	ds_read_b128 v[190:193], v229 offset:52224
	ds_read_b128 v[194:197], v229 offset:53248
	ds_read_b128 v[198:201], v229 offset:54272
	ds_read_b128 v[202:205], v229 offset:55296
	ds_read_b128 v[206:209], v229 offset:56320
	global_load_lds_dwordx4 v[210:211], off
	s_add_i32 m0, s22, 0x2000
	s_add_u32 s22, s62, 0x40080
	v_lshl_add_u64 v[210:211], v[212:213], 0, s[48:49]
	s_addc_u32 s23, s63, 0
	s_add_i32 s62, s81, s53
	global_load_lds_dwordx4 v[210:211], off
	v_lshl_add_u64 v[210:211], s[22:23], 0, v[130:131]
	s_mov_b32 m0, s62
	s_nop 0
	global_load_lds_dwordx4 v[210:211], off
	v_lshl_add_u64 v[210:211], s[22:23], 0, v[134:135]
	s_add_i32 m0, s62, 0x2000
	s_nop 0
	global_load_lds_dwordx4 v[210:211], off
	v_lshl_add_u64 v[210:211], v[214:215], 0, s[48:49]
	s_mov_b32 m0, s86
	s_nop 0
	global_load_lds_dwordx4 v[210:211], off
	v_lshl_add_u64 v[210:211], v[216:217], 0, s[48:49]
	s_mov_b32 m0, s87
	s_nop 0
	global_load_lds_dwordx4 v[210:211], off
	s_waitcnt vmcnt(8) lgkmcnt(0)
	s_barrier
	v_mfma_f32_16x16x32_bf16 v[60:63], v[146:149], v[178:181], v[60:63]
	v_mfma_f32_16x16x32_bf16 v[56:59], v[154:157], v[178:181], v[56:59]
	v_mfma_f32_16x16x32_bf16 v[52:55], v[146:149], v[186:189], v[52:55]
	v_mfma_f32_16x16x32_bf16 v[44:47], v[154:157], v[186:189], v[44:47]
	v_mfma_f32_16x16x32_bf16 v[36:39], v[146:149], v[194:197], v[36:39]
	v_mfma_f32_16x16x32_bf16 v[32:35], v[154:157], v[194:197], v[32:35]
	v_mfma_f32_16x16x32_bf16 v[20:23], v[146:149], v[202:205], v[20:23]
	v_mfma_f32_16x16x32_bf16 v[12:15], v[154:157], v[202:205], v[12:15]
	v_mfma_f32_16x16x32_bf16 v[60:63], v[150:153], v[182:185], v[60:63]
	v_mfma_f32_16x16x32_bf16 v[56:59], v[158:161], v[182:185], v[56:59]
	v_mfma_f32_16x16x32_bf16 v[52:55], v[150:153], v[190:193], v[52:55]
	v_mfma_f32_16x16x32_bf16 v[44:47], v[158:161], v[190:193], v[44:47]
	v_mfma_f32_16x16x32_bf16 v[36:39], v[150:153], v[198:201], v[36:39]
	v_mfma_f32_16x16x32_bf16 v[32:35], v[158:161], v[198:201], v[32:35]
	v_mfma_f32_16x16x32_bf16 v[20:23], v[150:153], v[206:209], v[20:23]
	v_mfma_f32_16x16x32_bf16 v[12:15], v[158:161], v[206:209], v[12:15]
	v_mfma_f32_16x16x32_bf16 v[48:51], v[162:165], v[178:181], v[48:51]
	v_mfma_f32_16x16x32_bf16 v[40:43], v[170:173], v[178:181], v[40:43]
	v_mfma_f32_16x16x32_bf16 v[28:31], v[162:165], v[186:189], v[28:31]
	v_mfma_f32_16x16x32_bf16 v[24:27], v[170:173], v[186:189], v[24:27]
	v_mfma_f32_16x16x32_bf16 v[16:19], v[162:165], v[194:197], v[16:19]
	v_mfma_f32_16x16x32_bf16 v[8:11], v[170:173], v[194:197], v[8:11]
	v_mfma_f32_16x16x32_bf16 v[4:7], v[162:165], v[202:205], v[4:7]
	v_mfma_f32_16x16x32_bf16 v[0:3], v[170:173], v[202:205], v[0:3]
	v_mfma_f32_16x16x32_bf16 v[48:51], v[166:169], v[182:185], v[48:51]
	v_mfma_f32_16x16x32_bf16 v[40:43], v[174:177], v[182:185], v[40:43]
	v_mfma_f32_16x16x32_bf16 v[28:31], v[166:169], v[190:193], v[28:31]
	v_mfma_f32_16x16x32_bf16 v[24:27], v[174:177], v[190:193], v[24:27]
	v_mfma_f32_16x16x32_bf16 v[16:19], v[166:169], v[198:201], v[16:19]
	v_mfma_f32_16x16x32_bf16 v[8:11], v[174:177], v[198:201], v[8:11]
	v_mfma_f32_16x16x32_bf16 v[4:7], v[166:169], v[206:209], v[4:7]
	v_mfma_f32_16x16x32_bf16 v[0:3], v[174:177], v[206:209], v[0:3]
	s_barrier
	s_add_i32 vcc_hi, vcc_hi, 2
	s_add_u32 s71, s71, 0x100
	s_addc_u32 vcc_lo, vcc_lo, 0
	s_add_u32 s12, s12, 0x100
	s_addc_u32 s13, s13, 0
	s_cmp_gt_u32 vcc_hi, 13
	s_cbranch_scc0 .LBB0_849
	s_and_b64 vcc, exec, s[50:51]
	s_cbranch_vccz .LBB0_852
	s_barrier

.LBB0_1059:
	ds_read_b128 v[144:147], v151
	ds_read_b128 v[154:157], v151 offset:1024
	ds_read_b128 v[158:161], v151 offset:2048
	ds_read_b128 v[162:165], v151 offset:3072
	ds_read_b128 v[166:169], v152
	ds_read_b128 v[170:173], v152 offset:1024
	ds_read_b128 v[174:177], v152 offset:2048
	ds_read_b128 v[178:181], v152 offset:3072
	s_add_u32 s46, s44, 0x100
	s_addc_u32 s47, s45, 0
	s_cmp_eq_u32 s71, 40
	s_cselect_b32 s51, s13, s47
	s_cselect_b32 s50, s12, s46
	s_cselect_b32 s49, s43, s27
	s_cselect_b32 s48, s42, s26
	v_lshl_add_u64 v[214:215], s[44:45], 0, v[138:139]
	s_add_i32 m0, s58, 0xc000
	ds_read_b128 v[182:185], v153
	ds_read_b128 v[186:189], v153 offset:1024
	ds_read_b128 v[190:193], v153 offset:2048
	ds_read_b128 v[194:197], v153 offset:3072
	ds_read_b128 v[198:201], v153 offset:4096
	ds_read_b128 v[202:205], v153 offset:5120
	ds_read_b128 v[206:209], v153 offset:6144
	ds_read_b128 v[210:213], v153 offset:7168
	global_load_lds_dwordx4 v[214:215], off
	v_lshl_add_u64 v[214:215], s[44:45], 0, v[136:137]
	s_add_i32 m0, s58, 0xe000
	s_nop 0
	global_load_lds_dwordx4 v[214:215], off
	s_waitcnt vmcnt(8) lgkmcnt(0)
	s_barrier
	v_mfma_f32_16x16x32_bf16 v[124:127], v[144:147], v[182:185], v[124:127]
	v_mfma_f32_16x16x32_bf16 v[120:123], v[158:161], v[182:185], v[120:123]
	v_mfma_f32_16x16x32_bf16 v[108:111], v[144:147], v[190:193], v[108:111]
	v_mfma_f32_16x16x32_bf16 v[104:107], v[158:161], v[190:193], v[104:107]
	v_mfma_f32_16x16x32_bf16 v[92:95], v[144:147], v[198:201], v[92:95]
	v_mfma_f32_16x16x32_bf16 v[88:91], v[158:161], v[198:201], v[88:91]
	v_mfma_f32_16x16x32_bf16 v[76:79], v[144:147], v[206:209], v[76:79]
	v_mfma_f32_16x16x32_bf16 v[72:75], v[158:161], v[206:209], v[72:75]
	v_mfma_f32_16x16x32_bf16 v[124:127], v[154:157], v[186:189], v[124:127]
	v_mfma_f32_16x16x32_bf16 v[120:123], v[162:165], v[186:189], v[120:123]
	v_mfma_f32_16x16x32_bf16 v[108:111], v[154:157], v[194:197], v[108:111]
	v_mfma_f32_16x16x32_bf16 v[104:107], v[162:165], v[194:197], v[104:107]
	v_mfma_f32_16x16x32_bf16 v[92:95], v[154:157], v[202:205], v[92:95]
	v_mfma_f32_16x16x32_bf16 v[88:91], v[162:165], v[202:205], v[88:91]
	v_mfma_f32_16x16x32_bf16 v[76:79], v[154:157], v[210:213], v[76:79]
	v_mfma_f32_16x16x32_bf16 v[72:75], v[162:165], v[210:213], v[72:75]
	v_mfma_f32_16x16x32_bf16 v[116:119], v[166:169], v[182:185], v[116:119]
	v_mfma_f32_16x16x32_bf16 v[112:115], v[174:177], v[182:185], v[112:115]
	v_mfma_f32_16x16x32_bf16 v[100:103], v[166:169], v[190:193], v[100:103]
	v_mfma_f32_16x16x32_bf16 v[96:99], v[174:177], v[190:193], v[96:99]
	v_mfma_f32_16x16x32_bf16 v[84:87], v[166:169], v[198:201], v[84:87]
	v_mfma_f32_16x16x32_bf16 v[80:83], v[174:177], v[198:201], v[80:83]
	v_mfma_f32_16x16x32_bf16 v[68:71], v[166:169], v[206:209], v[68:71]
	v_mfma_f32_16x16x32_bf16 v[64:67], v[174:177], v[206:209], v[64:67]
	v_mfma_f32_16x16x32_bf16 v[116:119], v[170:173], v[186:189], v[116:119]
	v_mfma_f32_16x16x32_bf16 v[112:115], v[178:181], v[186:189], v[112:115]
	v_mfma_f32_16x16x32_bf16 v[100:103], v[170:173], v[194:197], v[100:103]
	v_mfma_f32_16x16x32_bf16 v[96:99], v[178:181], v[194:197], v[96:99]
	v_mfma_f32_16x16x32_bf16 v[84:87], v[170:173], v[202:205], v[84:87]
	v_mfma_f32_16x16x32_bf16 v[80:83], v[178:181], v[202:205], v[80:83]
	v_mfma_f32_16x16x32_bf16 v[68:71], v[170:173], v[210:213], v[68:71]
	v_mfma_f32_16x16x32_bf16 v[64:67], v[178:181], v[210:213], v[64:67]
	s_barrier
	s_add_i32 s22, s67, s57
	v_lshl_add_u64 v[214:215], s[48:49], 0, v[130:131]
	s_mov_b32 m0, s22
	ds_read_b128 v[182:185], v153 offset:16384
	ds_read_b128 v[186:189], v153 offset:17408
	ds_read_b128 v[190:193], v153 offset:18432
	ds_read_b128 v[194:197], v153 offset:19456
	ds_read_b128 v[198:201], v153 offset:20480
	ds_read_b128 v[202:205], v153 offset:21504
	ds_read_b128 v[206:209], v153 offset:22528
	ds_read_b128 v[210:213], v153 offset:23552
	global_load_lds_dwordx4 v[214:215], off
	s_add_i32 m0, s22, 0x2000
	s_add_u32 s22, s48, 0xb0000
	v_lshl_add_u64 v[216:217], s[48:49], 0, v[134:135]
	s_addc_u32 s23, s49, 0
	s_add_i32 s44, s68, s57
	global_load_lds_dwordx4 v[216:217], off
	v_lshl_add_u64 v[218:219], s[22:23], 0, v[130:131]
	s_mov_b32 m0, s44
	v_lshl_add_u64 v[220:221], s[50:51], 0, v[132:133]
	global_load_lds_dwordx4 v[218:219], off
	v_lshl_add_u64 v[218:219], s[22:23], 0, v[134:135]
	s_add_i32 m0, s44, 0x2000
	s_nop 0
	global_load_lds_dwordx4 v[218:219], off
	v_lshl_add_u64 v[218:219], s[50:51], 0, v[128:129]
	s_mov_b32 m0, s58
	s_nop 0
	global_load_lds_dwordx4 v[218:219], off
	s_mov_b32 m0, s59
	s_nop 0
	global_load_lds_dwordx4 v[220:221], off
	s_waitcnt vmcnt(8) lgkmcnt(0)
	s_barrier
	v_mfma_f32_16x16x32_bf16 v[60:63], v[144:147], v[182:185], v[60:63]
	v_mfma_f32_16x16x32_bf16 v[56:59], v[158:161], v[182:185], v[56:59]
	v_mfma_f32_16x16x32_bf16 v[44:47], v[144:147], v[190:193], v[44:47]
	v_mfma_f32_16x16x32_bf16 v[40:43], v[158:161], v[190:193], v[40:43]
	v_mfma_f32_16x16x32_bf16 v[28:31], v[144:147], v[198:201], v[28:31]
	v_mfma_f32_16x16x32_bf16 v[24:27], v[158:161], v[198:201], v[24:27]
	v_mfma_f32_16x16x32_bf16 v[12:15], v[144:147], v[206:209], v[12:15]
	v_mfma_f32_16x16x32_bf16 v[8:11], v[158:161], v[206:209], v[8:11]
	v_mfma_f32_16x16x32_bf16 v[60:63], v[154:157], v[186:189], v[60:63]
	v_mfma_f32_16x16x32_bf16 v[56:59], v[162:165], v[186:189], v[56:59]
	v_mfma_f32_16x16x32_bf16 v[44:47], v[154:157], v[194:197], v[44:47]
	v_mfma_f32_16x16x32_bf16 v[40:43], v[162:165], v[194:197], v[40:43]
	v_mfma_f32_16x16x32_bf16 v[28:31], v[154:157], v[202:205], v[28:31]
	v_mfma_f32_16x16x32_bf16 v[24:27], v[162:165], v[202:205], v[24:27]
	v_mfma_f32_16x16x32_bf16 v[12:15], v[154:157], v[210:213], v[12:15]
	v_mfma_f32_16x16x32_bf16 v[8:11], v[162:165], v[210:213], v[8:11]
	v_mfma_f32_16x16x32_bf16 v[52:55], v[166:169], v[182:185], v[52:55]
	v_mfma_f32_16x16x32_bf16 v[48:51], v[174:177], v[182:185], v[48:51]
	v_mfma_f32_16x16x32_bf16 v[36:39], v[166:169], v[190:193], v[36:39]
	v_mfma_f32_16x16x32_bf16 v[32:35], v[174:177], v[190:193], v[32:35]
	v_mfma_f32_16x16x32_bf16 v[20:23], v[166:169], v[198:201], v[20:23]
	v_mfma_f32_16x16x32_bf16 v[16:19], v[174:177], v[198:201], v[16:19]
	v_mfma_f32_16x16x32_bf16 v[4:7], v[166:169], v[206:209], v[4:7]
	v_mfma_f32_16x16x32_bf16 v[0:3], v[174:177], v[206:209], v[0:3]
	v_mfma_f32_16x16x32_bf16 v[52:55], v[170:173], v[186:189], v[52:55]
	v_mfma_f32_16x16x32_bf16 v[48:51], v[178:181], v[186:189], v[48:51]
	v_mfma_f32_16x16x32_bf16 v[36:39], v[170:173], v[194:197], v[36:39]
	v_mfma_f32_16x16x32_bf16 v[32:35], v[178:181], v[194:197], v[32:35]
	v_mfma_f32_16x16x32_bf16 v[20:23], v[170:173], v[202:205], v[20:23]
	v_mfma_f32_16x16x32_bf16 v[16:19], v[178:181], v[202:205], v[16:19]
	v_mfma_f32_16x16x32_bf16 v[4:7], v[170:173], v[210:213], v[4:7]
	v_mfma_f32_16x16x32_bf16 v[0:3], v[178:181], v[210:213], v[0:3]
	s_barrier
	s_add_i32 s44, 0, 0x18000
	s_add_i32 s45, 0, 0x1c000
	v_add_u32_e32 v162, s44, v150
	v_add_u32_e32 v178, s45, v150
	ds_read_b128 v[144:147], v162
	ds_read_b128 v[154:157], v162 offset:1024
	ds_read_b128 v[158:161], v162 offset:2048
	ds_read_b128 v[162:165], v162 offset:3072
	ds_read_b128 v[166:169], v178
	ds_read_b128 v[170:173], v178 offset:1024
	ds_read_b128 v[174:177], v178 offset:2048
	ds_read_b128 v[178:181], v178 offset:3072
	s_add_u32 s22, s50, 0xb0000
	s_addc_u32 s23, s51, 0
	s_mov_b32 m0, s60
	v_lshl_add_u64 v[222:223], s[22:23], 0, v[128:129]
	ds_read_b128 v[182:185], v153 offset:32768
	ds_read_b128 v[186:189], v153 offset:33792
	ds_read_b128 v[190:193], v153 offset:34816
	ds_read_b128 v[194:197], v153 offset:35840
	ds_read_b128 v[198:201], v153 offset:36864
	ds_read_b128 v[202:205], v153 offset:37888
	ds_read_b128 v[206:209], v153 offset:38912
	ds_read_b128 v[210:213], v153 offset:39936
	global_load_lds_dwordx4 v[222:223], off
	v_lshl_add_u64 v[222:223], s[22:23], 0, v[132:133]
	s_mov_b32 m0, s61
	s_nop 0
	global_load_lds_dwordx4 v[222:223], off
	s_waitcnt vmcnt(8) lgkmcnt(0)
	s_barrier
	v_mfma_f32_16x16x32_bf16 v[124:127], v[144:147], v[182:185], v[124:127]
	v_mfma_f32_16x16x32_bf16 v[120:123], v[158:161], v[182:185], v[120:123]
	v_mfma_f32_16x16x32_bf16 v[108:111], v[144:147], v[190:193], v[108:111]
	v_mfma_f32_16x16x32_bf16 v[104:107], v[158:161], v[190:193], v[104:107]
	v_mfma_f32_16x16x32_bf16 v[92:95], v[144:147], v[198:201], v[92:95]
	v_mfma_f32_16x16x32_bf16 v[88:91], v[158:161], v[198:201], v[88:91]
	v_mfma_f32_16x16x32_bf16 v[76:79], v[144:147], v[206:209], v[76:79]
	v_mfma_f32_16x16x32_bf16 v[72:75], v[158:161], v[206:209], v[72:75]
	v_mfma_f32_16x16x32_bf16 v[124:127], v[154:157], v[186:189], v[124:127]
	v_mfma_f32_16x16x32_bf16 v[120:123], v[162:165], v[186:189], v[120:123]
	v_mfma_f32_16x16x32_bf16 v[108:111], v[154:157], v[194:197], v[108:111]
	v_mfma_f32_16x16x32_bf16 v[104:107], v[162:165], v[194:197], v[104:107]
	v_mfma_f32_16x16x32_bf16 v[92:95], v[154:157], v[202:205], v[92:95]
	v_mfma_f32_16x16x32_bf16 v[88:91], v[162:165], v[202:205], v[88:91]
	v_mfma_f32_16x16x32_bf16 v[76:79], v[154:157], v[210:213], v[76:79]
	v_mfma_f32_16x16x32_bf16 v[72:75], v[162:165], v[210:213], v[72:75]
	v_mfma_f32_16x16x32_bf16 v[116:119], v[166:169], v[182:185], v[116:119]
	v_mfma_f32_16x16x32_bf16 v[112:115], v[174:177], v[182:185], v[112:115]
	v_mfma_f32_16x16x32_bf16 v[100:103], v[166:169], v[190:193], v[100:103]
	v_mfma_f32_16x16x32_bf16 v[96:99], v[174:177], v[190:193], v[96:99]
	v_mfma_f32_16x16x32_bf16 v[84:87], v[166:169], v[198:201], v[84:87]
	v_mfma_f32_16x16x32_bf16 v[80:83], v[174:177], v[198:201], v[80:83]
	v_mfma_f32_16x16x32_bf16 v[68:71], v[166:169], v[206:209], v[68:71]
	v_mfma_f32_16x16x32_bf16 v[64:67], v[174:177], v[206:209], v[64:67]
	v_mfma_f32_16x16x32_bf16 v[116:119], v[170:173], v[186:189], v[116:119]
	v_mfma_f32_16x16x32_bf16 v[112:115], v[178:181], v[186:189], v[112:115]
	v_mfma_f32_16x16x32_bf16 v[100:103], v[170:173], v[194:197], v[100:103]
	v_mfma_f32_16x16x32_bf16 v[96:99], v[178:181], v[194:197], v[96:99]
	v_mfma_f32_16x16x32_bf16 v[84:87], v[170:173], v[202:205], v[84:87]
	v_mfma_f32_16x16x32_bf16 v[80:83], v[178:181], v[202:205], v[80:83]
	v_mfma_f32_16x16x32_bf16 v[68:71], v[170:173], v[210:213], v[68:71]
	v_mfma_f32_16x16x32_bf16 v[64:67], v[178:181], v[210:213], v[64:67]
	s_barrier
	s_add_i32 s22, s44, s57
	v_lshl_add_u64 v[214:215], v[214:215], 0, s[38:39]
	s_mov_b32 m0, s22
	ds_read_b128 v[182:185], v153 offset:49152
	ds_read_b128 v[186:189], v153 offset:50176
	ds_read_b128 v[190:193], v153 offset:51200
	ds_read_b128 v[194:197], v153 offset:52224
	ds_read_b128 v[198:201], v153 offset:53248
	ds_read_b128 v[202:205], v153 offset:54272
	ds_read_b128 v[206:209], v153 offset:55296
	ds_read_b128 v[210:213], v153 offset:56320
	global_load_lds_dwordx4 v[214:215], off
	s_add_i32 m0, s22, 0x2000
	s_add_u32 s22, s48, 0xb0080
	v_lshl_add_u64 v[214:215], v[216:217], 0, s[38:39]
	s_addc_u32 s23, s49, 0
	s_add_i32 s44, s45, s57
	global_load_lds_dwordx4 v[214:215], off
	v_lshl_add_u64 v[214:215], s[22:23], 0, v[130:131]
	s_mov_b32 m0, s44
	s_nop 0
	global_load_lds_dwordx4 v[214:215], off
	v_lshl_add_u64 v[214:215], s[22:23], 0, v[134:135]
	s_add_i32 m0, s44, 0x2000
	s_nop 0
	global_load_lds_dwordx4 v[214:215], off
	v_lshl_add_u64 v[214:215], v[218:219], 0, s[38:39]
	s_mov_b32 m0, s65
	s_nop 0
	global_load_lds_dwordx4 v[214:215], off
	v_lshl_add_u64 v[214:215], v[220:221], 0, s[38:39]
	s_mov_b32 m0, s66
	s_nop 0
	global_load_lds_dwordx4 v[214:215], off
	s_waitcnt vmcnt(8) lgkmcnt(0)
	s_barrier
	v_mfma_f32_16x16x32_bf16 v[60:63], v[144:147], v[182:185], v[60:63]
	v_mfma_f32_16x16x32_bf16 v[56:59], v[158:161], v[182:185], v[56:59]
	v_mfma_f32_16x16x32_bf16 v[44:47], v[144:147], v[190:193], v[44:47]
	v_mfma_f32_16x16x32_bf16 v[40:43], v[158:161], v[190:193], v[40:43]
	v_mfma_f32_16x16x32_bf16 v[28:31], v[144:147], v[198:201], v[28:31]
	v_mfma_f32_16x16x32_bf16 v[24:27], v[158:161], v[198:201], v[24:27]
	v_mfma_f32_16x16x32_bf16 v[12:15], v[144:147], v[206:209], v[12:15]
	v_mfma_f32_16x16x32_bf16 v[8:11], v[158:161], v[206:209], v[8:11]
	v_mfma_f32_16x16x32_bf16 v[60:63], v[154:157], v[186:189], v[60:63]
	v_mfma_f32_16x16x32_bf16 v[56:59], v[162:165], v[186:189], v[56:59]
	v_mfma_f32_16x16x32_bf16 v[44:47], v[154:157], v[194:197], v[44:47]
	v_mfma_f32_16x16x32_bf16 v[40:43], v[162:165], v[194:197], v[40:43]
	v_mfma_f32_16x16x32_bf16 v[28:31], v[154:157], v[202:205], v[28:31]
	v_mfma_f32_16x16x32_bf16 v[24:27], v[162:165], v[202:205], v[24:27]
	v_mfma_f32_16x16x32_bf16 v[12:15], v[154:157], v[210:213], v[12:15]
	v_mfma_f32_16x16x32_bf16 v[8:11], v[162:165], v[210:213], v[8:11]
	v_mfma_f32_16x16x32_bf16 v[52:55], v[166:169], v[182:185], v[52:55]
	v_mfma_f32_16x16x32_bf16 v[48:51], v[174:177], v[182:185], v[48:51]
	v_mfma_f32_16x16x32_bf16 v[36:39], v[166:169], v[190:193], v[36:39]
	v_mfma_f32_16x16x32_bf16 v[32:35], v[174:177], v[190:193], v[32:35]
	v_mfma_f32_16x16x32_bf16 v[20:23], v[166:169], v[198:201], v[20:23]
	v_mfma_f32_16x16x32_bf16 v[16:19], v[174:177], v[198:201], v[16:19]
	v_mfma_f32_16x16x32_bf16 v[4:7], v[166:169], v[206:209], v[4:7]
	v_mfma_f32_16x16x32_bf16 v[0:3], v[174:177], v[206:209], v[0:3]
	v_mfma_f32_16x16x32_bf16 v[52:55], v[170:173], v[186:189], v[52:55]
	v_mfma_f32_16x16x32_bf16 v[48:51], v[178:181], v[186:189], v[48:51]
	v_mfma_f32_16x16x32_bf16 v[36:39], v[170:173], v[194:197], v[36:39]
	v_mfma_f32_16x16x32_bf16 v[32:35], v[178:181], v[194:197], v[32:35]
	v_mfma_f32_16x16x32_bf16 v[20:23], v[170:173], v[202:205], v[20:23]
	v_mfma_f32_16x16x32_bf16 v[16:19], v[178:181], v[202:205], v[16:19]
	v_mfma_f32_16x16x32_bf16 v[4:7], v[170:173], v[210:213], v[4:7]
	v_mfma_f32_16x16x32_bf16 v[0:3], v[178:181], v[210:213], v[0:3]
	s_barrier
	s_add_i32 s71, s71, 2
	s_add_u32 s26, s26, 0x100
	s_addc_u32 s27, s27, 0
	s_cmp_gt_u32 s71, 41
	s_mov_b64 s[44:45], s[46:47]
	s_cbranch_scc0 .LBB0_1059
	s_and_b64 vcc, exec, s[40:41]
	s_cbranch_vccz .LBB0_1062
	s_barrier

.LBB0_1161:
	ds_read_b128 v[144:147], v155
	ds_read_b128 v[148:151], v155 offset:1024
	ds_read_b128 v[158:161], v155 offset:2048
	ds_read_b128 v[162:165], v155 offset:3072
	ds_read_b128 v[166:169], v156
	ds_read_b128 v[170:173], v156 offset:1024
	ds_read_b128 v[174:177], v156 offset:2048
	ds_read_b128 v[178:181], v156 offset:3072
	s_add_u32 s22, s58, 0xfffc0080
	s_addc_u32 s23, s59, -1
	s_cmp_eq_u32 s94, 12
	s_cselect_b32 s63, s13, s23
	s_cselect_b32 s62, s26, s22
	s_cselect_b32 s61, s27, s57
	s_cselect_b32 s60, s49, s51
	v_lshl_add_u64 v[214:215], s[58:59], 0, v[138:139]
	s_add_i32 m0, s71, 0xc000
	ds_read_b128 v[182:185], v157
	ds_read_b128 v[186:189], v157 offset:1024
	ds_read_b128 v[190:193], v157 offset:2048
	ds_read_b128 v[194:197], v157 offset:3072
	ds_read_b128 v[198:201], v157 offset:4096
	ds_read_b128 v[202:205], v157 offset:5120
	ds_read_b128 v[206:209], v157 offset:6144
	ds_read_b128 v[210:213], v157 offset:7168
	global_load_lds_dwordx4 v[214:215], off
	v_lshl_add_u64 v[214:215], s[58:59], 0, v[136:137]
	s_add_i32 m0, s71, 0xe000
	s_nop 0
	global_load_lds_dwordx4 v[214:215], off
	s_waitcnt vmcnt(8) lgkmcnt(0)
	s_barrier
	v_mfma_f32_16x16x32_bf16 v[124:127], v[144:147], v[182:185], v[124:127]
	v_mfma_f32_16x16x32_bf16 v[120:123], v[158:161], v[182:185], v[120:123]
	v_mfma_f32_16x16x32_bf16 v[108:111], v[144:147], v[190:193], v[108:111]
	v_mfma_f32_16x16x32_bf16 v[104:107], v[158:161], v[190:193], v[104:107]
	v_mfma_f32_16x16x32_bf16 v[92:95], v[144:147], v[198:201], v[92:95]
	v_mfma_f32_16x16x32_bf16 v[88:91], v[158:161], v[198:201], v[88:91]
	v_mfma_f32_16x16x32_bf16 v[76:79], v[144:147], v[206:209], v[76:79]
	v_mfma_f32_16x16x32_bf16 v[72:75], v[158:161], v[206:209], v[72:75]
	v_mfma_f32_16x16x32_bf16 v[124:127], v[148:151], v[186:189], v[124:127]
	v_mfma_f32_16x16x32_bf16 v[120:123], v[162:165], v[186:189], v[120:123]
	v_mfma_f32_16x16x32_bf16 v[108:111], v[148:151], v[194:197], v[108:111]
	v_mfma_f32_16x16x32_bf16 v[104:107], v[162:165], v[194:197], v[104:107]
	v_mfma_f32_16x16x32_bf16 v[92:95], v[148:151], v[202:205], v[92:95]
	v_mfma_f32_16x16x32_bf16 v[88:91], v[162:165], v[202:205], v[88:91]
	v_mfma_f32_16x16x32_bf16 v[76:79], v[148:151], v[210:213], v[76:79]
	v_mfma_f32_16x16x32_bf16 v[72:75], v[162:165], v[210:213], v[72:75]
	v_mfma_f32_16x16x32_bf16 v[116:119], v[166:169], v[182:185], v[116:119]
	v_mfma_f32_16x16x32_bf16 v[112:115], v[174:177], v[182:185], v[112:115]
	v_mfma_f32_16x16x32_bf16 v[100:103], v[166:169], v[190:193], v[100:103]
	v_mfma_f32_16x16x32_bf16 v[96:99], v[174:177], v[190:193], v[96:99]
	v_mfma_f32_16x16x32_bf16 v[84:87], v[166:169], v[198:201], v[84:87]
	v_mfma_f32_16x16x32_bf16 v[80:83], v[174:177], v[198:201], v[80:83]
	v_mfma_f32_16x16x32_bf16 v[68:71], v[166:169], v[206:209], v[68:71]
	v_mfma_f32_16x16x32_bf16 v[64:67], v[174:177], v[206:209], v[64:67]
	v_mfma_f32_16x16x32_bf16 v[116:119], v[170:173], v[186:189], v[116:119]
	v_mfma_f32_16x16x32_bf16 v[112:115], v[178:181], v[186:189], v[112:115]
	v_mfma_f32_16x16x32_bf16 v[100:103], v[170:173], v[194:197], v[100:103]
	v_mfma_f32_16x16x32_bf16 v[96:99], v[178:181], v[194:197], v[96:99]
	v_mfma_f32_16x16x32_bf16 v[84:87], v[170:173], v[202:205], v[84:87]
	v_mfma_f32_16x16x32_bf16 v[80:83], v[178:181], v[202:205], v[80:83]
	v_mfma_f32_16x16x32_bf16 v[68:71], v[170:173], v[210:213], v[68:71]
	v_mfma_f32_16x16x32_bf16 v[64:67], v[178:181], v[210:213], v[64:67]
	s_barrier
	s_add_i32 s22, s91, s65
	v_lshl_add_u64 v[214:215], s[60:61], 0, v[130:131]
	s_mov_b32 m0, s22
	ds_read_b128 v[182:185], v157 offset:16384
	ds_read_b128 v[186:189], v157 offset:17408
	ds_read_b128 v[190:193], v157 offset:18432
	ds_read_b128 v[194:197], v157 offset:19456
	ds_read_b128 v[198:201], v157 offset:20480
	ds_read_b128 v[202:205], v157 offset:21504
	ds_read_b128 v[206:209], v157 offset:22528
	ds_read_b128 v[210:213], v157 offset:23552
	global_load_lds_dwordx4 v[214:215], off
	s_add_i32 m0, s22, 0x2000
	s_add_u32 s22, s60, 0x40000
	v_lshl_add_u64 v[216:217], s[60:61], 0, v[134:135]
	s_addc_u32 s23, s61, 0
	s_add_i32 s70, s92, s65
	global_load_lds_dwordx4 v[216:217], off
	v_lshl_add_u64 v[218:219], s[22:23], 0, v[130:131]
	s_mov_b32 m0, s70
	v_lshl_add_u64 v[220:221], s[62:63], 0, v[132:133]
	global_load_lds_dwordx4 v[218:219], off
	v_lshl_add_u64 v[218:219], s[22:23], 0, v[134:135]
	s_add_i32 m0, s70, 0x2000
	s_nop 0
	global_load_lds_dwordx4 v[218:219], off
	v_lshl_add_u64 v[218:219], s[62:63], 0, v[128:129]
	s_mov_b32 m0, s71
	s_nop 0
	global_load_lds_dwordx4 v[218:219], off
	s_mov_b32 m0, s82
	s_nop 0
	global_load_lds_dwordx4 v[220:221], off
	s_waitcnt vmcnt(8) lgkmcnt(0)
	s_barrier
	v_mfma_f32_16x16x32_bf16 v[60:63], v[144:147], v[182:185], v[60:63]
	v_mfma_f32_16x16x32_bf16 v[56:59], v[158:161], v[182:185], v[56:59]
	v_mfma_f32_16x16x32_bf16 v[44:47], v[144:147], v[190:193], v[44:47]
	v_mfma_f32_16x16x32_bf16 v[40:43], v[158:161], v[190:193], v[40:43]
	v_mfma_f32_16x16x32_bf16 v[28:31], v[144:147], v[198:201], v[28:31]
	v_mfma_f32_16x16x32_bf16 v[24:27], v[158:161], v[198:201], v[24:27]
	v_mfma_f32_16x16x32_bf16 v[12:15], v[144:147], v[206:209], v[12:15]
	v_mfma_f32_16x16x32_bf16 v[8:11], v[158:161], v[206:209], v[8:11]
	v_mfma_f32_16x16x32_bf16 v[60:63], v[148:151], v[186:189], v[60:63]
	v_mfma_f32_16x16x32_bf16 v[56:59], v[162:165], v[186:189], v[56:59]
	v_mfma_f32_16x16x32_bf16 v[44:47], v[148:151], v[194:197], v[44:47]
	v_mfma_f32_16x16x32_bf16 v[40:43], v[162:165], v[194:197], v[40:43]
	v_mfma_f32_16x16x32_bf16 v[28:31], v[148:151], v[202:205], v[28:31]
	v_mfma_f32_16x16x32_bf16 v[24:27], v[162:165], v[202:205], v[24:27]
	v_mfma_f32_16x16x32_bf16 v[12:15], v[148:151], v[210:213], v[12:15]
	v_mfma_f32_16x16x32_bf16 v[8:11], v[162:165], v[210:213], v[8:11]
	v_mfma_f32_16x16x32_bf16 v[52:55], v[166:169], v[182:185], v[52:55]
	v_mfma_f32_16x16x32_bf16 v[48:51], v[174:177], v[182:185], v[48:51]
	v_mfma_f32_16x16x32_bf16 v[36:39], v[166:169], v[190:193], v[36:39]
	v_mfma_f32_16x16x32_bf16 v[32:35], v[174:177], v[190:193], v[32:35]
	v_mfma_f32_16x16x32_bf16 v[20:23], v[166:169], v[198:201], v[20:23]
	v_mfma_f32_16x16x32_bf16 v[16:19], v[174:177], v[198:201], v[16:19]
	v_mfma_f32_16x16x32_bf16 v[4:7], v[166:169], v[206:209], v[4:7]
	v_mfma_f32_16x16x32_bf16 v[0:3], v[174:177], v[206:209], v[0:3]
	v_mfma_f32_16x16x32_bf16 v[52:55], v[170:173], v[186:189], v[52:55]
	v_mfma_f32_16x16x32_bf16 v[48:51], v[178:181], v[186:189], v[48:51]
	v_mfma_f32_16x16x32_bf16 v[36:39], v[170:173], v[194:197], v[36:39]
	v_mfma_f32_16x16x32_bf16 v[32:35], v[178:181], v[194:197], v[32:35]
	v_mfma_f32_16x16x32_bf16 v[20:23], v[170:173], v[202:205], v[20:23]
	v_mfma_f32_16x16x32_bf16 v[16:19], v[178:181], v[202:205], v[16:19]
	v_mfma_f32_16x16x32_bf16 v[4:7], v[170:173], v[210:213], v[4:7]
	v_mfma_f32_16x16x32_bf16 v[0:3], v[178:181], v[210:213], v[0:3]
	s_barrier
	s_add_i32 s70, 0, 0x18000
	s_add_i32 s81, 0, 0x1c000
	v_add_u32_e32 v162, s70, v154
	v_add_u32_e32 v178, s81, v154
	ds_read_b128 v[144:147], v162
	ds_read_b128 v[148:151], v162 offset:1024
	ds_read_b128 v[158:161], v162 offset:2048
	ds_read_b128 v[162:165], v162 offset:3072
	ds_read_b128 v[166:169], v178
	ds_read_b128 v[170:173], v178 offset:1024
	ds_read_b128 v[174:177], v178 offset:2048
	ds_read_b128 v[178:181], v178 offset:3072
	s_add_u32 s22, s62, 0x40000
	s_addc_u32 s23, s63, 0
	s_mov_b32 m0, s83
	v_lshl_add_u64 v[222:223], s[22:23], 0, v[128:129]
	ds_read_b128 v[182:185], v157 offset:32768
	ds_read_b128 v[186:189], v157 offset:33792
	ds_read_b128 v[190:193], v157 offset:34816
	ds_read_b128 v[194:197], v157 offset:35840
	ds_read_b128 v[198:201], v157 offset:36864
	ds_read_b128 v[202:205], v157 offset:37888
	ds_read_b128 v[206:209], v157 offset:38912
	ds_read_b128 v[210:213], v157 offset:39936
	global_load_lds_dwordx4 v[222:223], off
	v_lshl_add_u64 v[222:223], s[22:23], 0, v[132:133]
	s_mov_b32 m0, s84
	s_nop 0
	global_load_lds_dwordx4 v[222:223], off
	s_waitcnt vmcnt(8) lgkmcnt(0)
	s_barrier
	v_mfma_f32_16x16x32_bf16 v[124:127], v[144:147], v[182:185], v[124:127]
	v_mfma_f32_16x16x32_bf16 v[120:123], v[158:161], v[182:185], v[120:123]
	v_mfma_f32_16x16x32_bf16 v[108:111], v[144:147], v[190:193], v[108:111]
	v_mfma_f32_16x16x32_bf16 v[104:107], v[158:161], v[190:193], v[104:107]
	v_mfma_f32_16x16x32_bf16 v[92:95], v[144:147], v[198:201], v[92:95]
	v_mfma_f32_16x16x32_bf16 v[88:91], v[158:161], v[198:201], v[88:91]
	v_mfma_f32_16x16x32_bf16 v[76:79], v[144:147], v[206:209], v[76:79]
	v_mfma_f32_16x16x32_bf16 v[72:75], v[158:161], v[206:209], v[72:75]
	v_mfma_f32_16x16x32_bf16 v[124:127], v[148:151], v[186:189], v[124:127]
	v_mfma_f32_16x16x32_bf16 v[120:123], v[162:165], v[186:189], v[120:123]
	v_mfma_f32_16x16x32_bf16 v[108:111], v[148:151], v[194:197], v[108:111]
	v_mfma_f32_16x16x32_bf16 v[104:107], v[162:165], v[194:197], v[104:107]
	v_mfma_f32_16x16x32_bf16 v[92:95], v[148:151], v[202:205], v[92:95]
	v_mfma_f32_16x16x32_bf16 v[88:91], v[162:165], v[202:205], v[88:91]
	v_mfma_f32_16x16x32_bf16 v[76:79], v[148:151], v[210:213], v[76:79]
	v_mfma_f32_16x16x32_bf16 v[72:75], v[162:165], v[210:213], v[72:75]
	v_mfma_f32_16x16x32_bf16 v[116:119], v[166:169], v[182:185], v[116:119]
	v_mfma_f32_16x16x32_bf16 v[112:115], v[174:177], v[182:185], v[112:115]
	v_mfma_f32_16x16x32_bf16 v[100:103], v[166:169], v[190:193], v[100:103]
	v_mfma_f32_16x16x32_bf16 v[96:99], v[174:177], v[190:193], v[96:99]
	v_mfma_f32_16x16x32_bf16 v[84:87], v[166:169], v[198:201], v[84:87]
	v_mfma_f32_16x16x32_bf16 v[80:83], v[174:177], v[198:201], v[80:83]
	v_mfma_f32_16x16x32_bf16 v[68:71], v[166:169], v[206:209], v[68:71]
	v_mfma_f32_16x16x32_bf16 v[64:67], v[174:177], v[206:209], v[64:67]
	v_mfma_f32_16x16x32_bf16 v[116:119], v[170:173], v[186:189], v[116:119]
	v_mfma_f32_16x16x32_bf16 v[112:115], v[178:181], v[186:189], v[112:115]
	v_mfma_f32_16x16x32_bf16 v[100:103], v[170:173], v[194:197], v[100:103]
	v_mfma_f32_16x16x32_bf16 v[96:99], v[178:181], v[194:197], v[96:99]
	v_mfma_f32_16x16x32_bf16 v[84:87], v[170:173], v[202:205], v[84:87]
	v_mfma_f32_16x16x32_bf16 v[80:83], v[178:181], v[202:205], v[80:83]
	v_mfma_f32_16x16x32_bf16 v[68:71], v[170:173], v[210:213], v[68:71]
	v_mfma_f32_16x16x32_bf16 v[64:67], v[178:181], v[210:213], v[64:67]
	s_barrier
	s_add_i32 s22, s70, s65
	v_lshl_add_u64 v[214:215], v[214:215], 0, s[44:45]
	s_mov_b32 m0, s22
	ds_read_b128 v[182:185], v157 offset:49152
	ds_read_b128 v[186:189], v157 offset:50176
	ds_read_b128 v[190:193], v157 offset:51200
	ds_read_b128 v[194:197], v157 offset:52224
	ds_read_b128 v[198:201], v157 offset:53248
	ds_read_b128 v[202:205], v157 offset:54272
	ds_read_b128 v[206:209], v157 offset:55296
	ds_read_b128 v[210:213], v157 offset:56320
	global_load_lds_dwordx4 v[214:215], off
	s_add_i32 m0, s22, 0x2000
	s_add_u32 s22, s60, 0x40080
	v_lshl_add_u64 v[214:215], v[216:217], 0, s[44:45]
	s_addc_u32 s23, s61, 0
	s_add_i32 s60, s81, s65
	global_load_lds_dwordx4 v[214:215], off
	v_lshl_add_u64 v[214:215], s[22:23], 0, v[130:131]
	s_mov_b32 m0, s60
	s_nop 0
	global_load_lds_dwordx4 v[214:215], off
	v_lshl_add_u64 v[214:215], s[22:23], 0, v[134:135]
	s_add_i32 m0, s60, 0x2000
	s_nop 0
	global_load_lds_dwordx4 v[214:215], off
	v_lshl_add_u64 v[214:215], v[218:219], 0, s[44:45]
	s_mov_b32 m0, s88
	s_nop 0
	global_load_lds_dwordx4 v[214:215], off
	v_lshl_add_u64 v[214:215], v[220:221], 0, s[44:45]
	s_mov_b32 m0, s89
	s_nop 0
	global_load_lds_dwordx4 v[214:215], off
	s_waitcnt vmcnt(8) lgkmcnt(0)
	s_barrier
	v_mfma_f32_16x16x32_bf16 v[60:63], v[144:147], v[182:185], v[60:63]
	v_mfma_f32_16x16x32_bf16 v[56:59], v[158:161], v[182:185], v[56:59]
	v_mfma_f32_16x16x32_bf16 v[44:47], v[144:147], v[190:193], v[44:47]
	v_mfma_f32_16x16x32_bf16 v[40:43], v[158:161], v[190:193], v[40:43]
	v_mfma_f32_16x16x32_bf16 v[28:31], v[144:147], v[198:201], v[28:31]
	v_mfma_f32_16x16x32_bf16 v[24:27], v[158:161], v[198:201], v[24:27]
	v_mfma_f32_16x16x32_bf16 v[12:15], v[144:147], v[206:209], v[12:15]
	v_mfma_f32_16x16x32_bf16 v[8:11], v[158:161], v[206:209], v[8:11]
	v_mfma_f32_16x16x32_bf16 v[60:63], v[148:151], v[186:189], v[60:63]
	v_mfma_f32_16x16x32_bf16 v[56:59], v[162:165], v[186:189], v[56:59]
	v_mfma_f32_16x16x32_bf16 v[44:47], v[148:151], v[194:197], v[44:47]
	v_mfma_f32_16x16x32_bf16 v[40:43], v[162:165], v[194:197], v[40:43]
	v_mfma_f32_16x16x32_bf16 v[28:31], v[148:151], v[202:205], v[28:31]
	v_mfma_f32_16x16x32_bf16 v[24:27], v[162:165], v[202:205], v[24:27]
	v_mfma_f32_16x16x32_bf16 v[12:15], v[148:151], v[210:213], v[12:15]
	v_mfma_f32_16x16x32_bf16 v[8:11], v[162:165], v[210:213], v[8:11]
	v_mfma_f32_16x16x32_bf16 v[52:55], v[166:169], v[182:185], v[52:55]
	v_mfma_f32_16x16x32_bf16 v[48:51], v[174:177], v[182:185], v[48:51]
	v_mfma_f32_16x16x32_bf16 v[36:39], v[166:169], v[190:193], v[36:39]
	v_mfma_f32_16x16x32_bf16 v[32:35], v[174:177], v[190:193], v[32:35]
	v_mfma_f32_16x16x32_bf16 v[20:23], v[166:169], v[198:201], v[20:23]
	v_mfma_f32_16x16x32_bf16 v[16:19], v[174:177], v[198:201], v[16:19]
	v_mfma_f32_16x16x32_bf16 v[4:7], v[166:169], v[206:209], v[4:7]
	v_mfma_f32_16x16x32_bf16 v[0:3], v[174:177], v[206:209], v[0:3]
	v_mfma_f32_16x16x32_bf16 v[52:55], v[170:173], v[186:189], v[52:55]
	v_mfma_f32_16x16x32_bf16 v[48:51], v[178:181], v[186:189], v[48:51]
	v_mfma_f32_16x16x32_bf16 v[36:39], v[170:173], v[194:197], v[36:39]
	v_mfma_f32_16x16x32_bf16 v[32:35], v[178:181], v[194:197], v[32:35]
	v_mfma_f32_16x16x32_bf16 v[20:23], v[170:173], v[202:205], v[20:23]
	v_mfma_f32_16x16x32_bf16 v[16:19], v[178:181], v[202:205], v[16:19]
	v_mfma_f32_16x16x32_bf16 v[4:7], v[170:173], v[210:213], v[4:7]
	v_mfma_f32_16x16x32_bf16 v[0:3], v[178:181], v[210:213], v[0:3]
	s_barrier
	s_add_i32 s94, s94, 2
	s_add_u32 s51, s51, 0x100
	s_addc_u32 s57, s57, 0
	s_add_u32 s58, s58, 0x100
	s_addc_u32 s59, s59, 0
	s_cmp_gt_u32 s94, 13
	s_cbranch_scc0 .LBB0_1161
	s_and_b64 vcc, exec, s[46:47]
	s_cbranch_vccz .LBB0_1164
	s_barrier

.LBB0_1603:
	ds_read_b128 v[144:147], v151
	ds_read_b128 v[154:157], v151 offset:1024
	ds_read_b128 v[158:161], v151 offset:2048
	ds_read_b128 v[162:165], v151 offset:3072
	ds_read_b128 v[166:169], v152
	ds_read_b128 v[170:173], v152 offset:1024
	ds_read_b128 v[174:177], v152 offset:2048
	ds_read_b128 v[178:181], v152 offset:3072
	s_add_u32 s48, s46, 0xfffc0080
	s_addc_u32 s49, s47, -1
	s_cmp_eq_u32 s71, 12
	s_cselect_b32 s51, s26, s49
	s_cselect_b32 s50, s27, s48
	s_cselect_b32 s49, s39, s69
	s_cselect_b32 s48, s41, s68
	v_lshl_add_u64 v[214:215], s[46:47], 0, v[138:139]
	s_add_i32 m0, s15, 0xc000
	ds_read_b128 v[182:185], v153
	ds_read_b128 v[186:189], v153 offset:1024
	ds_read_b128 v[190:193], v153 offset:2048
	ds_read_b128 v[194:197], v153 offset:3072
	ds_read_b128 v[198:201], v153 offset:4096
	ds_read_b128 v[202:205], v153 offset:5120
	ds_read_b128 v[206:209], v153 offset:6144
	ds_read_b128 v[210:213], v153 offset:7168
	global_load_lds_dwordx4 v[214:215], off
	v_lshl_add_u64 v[214:215], s[46:47], 0, v[136:137]
	s_add_i32 m0, s15, 0xe000
	s_nop 0
	global_load_lds_dwordx4 v[214:215], off
	s_waitcnt vmcnt(8) lgkmcnt(0)
	s_barrier
	v_mfma_f32_16x16x32_bf16 v[124:127], v[144:147], v[182:185], v[124:127]
	v_mfma_f32_16x16x32_bf16 v[120:123], v[158:161], v[182:185], v[120:123]
	v_mfma_f32_16x16x32_bf16 v[108:111], v[144:147], v[190:193], v[108:111]
	v_mfma_f32_16x16x32_bf16 v[104:107], v[158:161], v[190:193], v[104:107]
	v_mfma_f32_16x16x32_bf16 v[92:95], v[144:147], v[198:201], v[92:95]
	v_mfma_f32_16x16x32_bf16 v[88:91], v[158:161], v[198:201], v[88:91]
	v_mfma_f32_16x16x32_bf16 v[76:79], v[144:147], v[206:209], v[76:79]
	v_mfma_f32_16x16x32_bf16 v[72:75], v[158:161], v[206:209], v[72:75]
	v_mfma_f32_16x16x32_bf16 v[124:127], v[154:157], v[186:189], v[124:127]
	v_mfma_f32_16x16x32_bf16 v[120:123], v[162:165], v[186:189], v[120:123]
	v_mfma_f32_16x16x32_bf16 v[108:111], v[154:157], v[194:197], v[108:111]
	v_mfma_f32_16x16x32_bf16 v[104:107], v[162:165], v[194:197], v[104:107]
	v_mfma_f32_16x16x32_bf16 v[92:95], v[154:157], v[202:205], v[92:95]
	v_mfma_f32_16x16x32_bf16 v[88:91], v[162:165], v[202:205], v[88:91]
	v_mfma_f32_16x16x32_bf16 v[76:79], v[154:157], v[210:213], v[76:79]
	v_mfma_f32_16x16x32_bf16 v[72:75], v[162:165], v[210:213], v[72:75]
	v_mfma_f32_16x16x32_bf16 v[116:119], v[166:169], v[182:185], v[116:119]
	v_mfma_f32_16x16x32_bf16 v[112:115], v[174:177], v[182:185], v[112:115]
	v_mfma_f32_16x16x32_bf16 v[100:103], v[166:169], v[190:193], v[100:103]
	v_mfma_f32_16x16x32_bf16 v[96:99], v[174:177], v[190:193], v[96:99]
	v_mfma_f32_16x16x32_bf16 v[84:87], v[166:169], v[198:201], v[84:87]
	v_mfma_f32_16x16x32_bf16 v[80:83], v[174:177], v[198:201], v[80:83]
	v_mfma_f32_16x16x32_bf16 v[68:71], v[166:169], v[206:209], v[68:71]
	v_mfma_f32_16x16x32_bf16 v[64:67], v[174:177], v[206:209], v[64:67]
	v_mfma_f32_16x16x32_bf16 v[116:119], v[170:173], v[186:189], v[116:119]
	v_mfma_f32_16x16x32_bf16 v[112:115], v[178:181], v[186:189], v[112:115]
	v_mfma_f32_16x16x32_bf16 v[100:103], v[170:173], v[194:197], v[100:103]
	v_mfma_f32_16x16x32_bf16 v[96:99], v[178:181], v[194:197], v[96:99]
	v_mfma_f32_16x16x32_bf16 v[84:87], v[170:173], v[202:205], v[84:87]
	v_mfma_f32_16x16x32_bf16 v[80:83], v[178:181], v[202:205], v[80:83]
	v_mfma_f32_16x16x32_bf16 v[68:71], v[170:173], v[210:213], v[68:71]
	v_mfma_f32_16x16x32_bf16 v[64:67], v[178:181], v[210:213], v[64:67]
	s_barrier
	s_add_i32 s70, s65, s56
	v_lshl_add_u64 v[214:215], s[48:49], 0, v[130:131]
	s_mov_b32 m0, s70
	ds_read_b128 v[182:185], v153 offset:16384
	ds_read_b128 v[186:189], v153 offset:17408
	ds_read_b128 v[190:193], v153 offset:18432
	ds_read_b128 v[194:197], v153 offset:19456
	ds_read_b128 v[198:201], v153 offset:20480
	ds_read_b128 v[202:205], v153 offset:21504
	ds_read_b128 v[206:209], v153 offset:22528
	ds_read_b128 v[210:213], v153 offset:23552
	global_load_lds_dwordx4 v[214:215], off
	s_add_i32 m0, s70, 0x2000
	s_add_u32 s78, s48, 0x40000
	v_lshl_add_u64 v[216:217], s[48:49], 0, v[134:135]
	s_addc_u32 s79, s49, 0
	s_add_i32 s70, s66, s56
	global_load_lds_dwordx4 v[216:217], off
	v_lshl_add_u64 v[218:219], s[78:79], 0, v[130:131]
	s_mov_b32 m0, s70
	v_lshl_add_u64 v[220:221], s[50:51], 0, v[132:133]
	global_load_lds_dwordx4 v[218:219], off
	v_lshl_add_u64 v[218:219], s[78:79], 0, v[134:135]
	s_add_i32 m0, s70, 0x2000
	s_nop 0
	global_load_lds_dwordx4 v[218:219], off
	v_lshl_add_u64 v[218:219], s[50:51], 0, v[128:129]
	s_mov_b32 m0, s15
	s_nop 0
	global_load_lds_dwordx4 v[218:219], off
	s_mov_b32 m0, s57
	s_nop 0
	global_load_lds_dwordx4 v[220:221], off
	s_waitcnt vmcnt(8) lgkmcnt(0)
	s_barrier
	v_mfma_f32_16x16x32_bf16 v[60:63], v[144:147], v[182:185], v[60:63]
	v_mfma_f32_16x16x32_bf16 v[56:59], v[158:161], v[182:185], v[56:59]
	v_mfma_f32_16x16x32_bf16 v[44:47], v[144:147], v[190:193], v[44:47]
	v_mfma_f32_16x16x32_bf16 v[40:43], v[158:161], v[190:193], v[40:43]
	v_mfma_f32_16x16x32_bf16 v[28:31], v[144:147], v[198:201], v[28:31]
	v_mfma_f32_16x16x32_bf16 v[24:27], v[158:161], v[198:201], v[24:27]
	v_mfma_f32_16x16x32_bf16 v[12:15], v[144:147], v[206:209], v[12:15]
	v_mfma_f32_16x16x32_bf16 v[8:11], v[158:161], v[206:209], v[8:11]
	v_mfma_f32_16x16x32_bf16 v[60:63], v[154:157], v[186:189], v[60:63]
	v_mfma_f32_16x16x32_bf16 v[56:59], v[162:165], v[186:189], v[56:59]
	v_mfma_f32_16x16x32_bf16 v[44:47], v[154:157], v[194:197], v[44:47]
	v_mfma_f32_16x16x32_bf16 v[40:43], v[162:165], v[194:197], v[40:43]
	v_mfma_f32_16x16x32_bf16 v[28:31], v[154:157], v[202:205], v[28:31]
	v_mfma_f32_16x16x32_bf16 v[24:27], v[162:165], v[202:205], v[24:27]
	v_mfma_f32_16x16x32_bf16 v[12:15], v[154:157], v[210:213], v[12:15]
	v_mfma_f32_16x16x32_bf16 v[8:11], v[162:165], v[210:213], v[8:11]
	v_mfma_f32_16x16x32_bf16 v[52:55], v[166:169], v[182:185], v[52:55]
	v_mfma_f32_16x16x32_bf16 v[48:51], v[174:177], v[182:185], v[48:51]
	v_mfma_f32_16x16x32_bf16 v[36:39], v[166:169], v[190:193], v[36:39]
	v_mfma_f32_16x16x32_bf16 v[32:35], v[174:177], v[190:193], v[32:35]
	v_mfma_f32_16x16x32_bf16 v[20:23], v[166:169], v[198:201], v[20:23]
	v_mfma_f32_16x16x32_bf16 v[16:19], v[174:177], v[198:201], v[16:19]
	v_mfma_f32_16x16x32_bf16 v[4:7], v[166:169], v[206:209], v[4:7]
	v_mfma_f32_16x16x32_bf16 v[0:3], v[174:177], v[206:209], v[0:3]
	v_mfma_f32_16x16x32_bf16 v[52:55], v[170:173], v[186:189], v[52:55]
	v_mfma_f32_16x16x32_bf16 v[48:51], v[178:181], v[186:189], v[48:51]
	v_mfma_f32_16x16x32_bf16 v[36:39], v[170:173], v[194:197], v[36:39]
	v_mfma_f32_16x16x32_bf16 v[32:35], v[178:181], v[194:197], v[32:35]
	v_mfma_f32_16x16x32_bf16 v[20:23], v[170:173], v[202:205], v[20:23]
	v_mfma_f32_16x16x32_bf16 v[16:19], v[178:181], v[202:205], v[16:19]
	v_mfma_f32_16x16x32_bf16 v[4:7], v[170:173], v[210:213], v[4:7]
	v_mfma_f32_16x16x32_bf16 v[0:3], v[178:181], v[210:213], v[0:3]
	s_barrier
	s_add_i32 s70, 0, 0x18000
	s_add_i32 s77, 0, 0x1c000
	v_add_u32_e32 v162, s70, v150
	v_add_u32_e32 v178, s77, v150
	ds_read_b128 v[144:147], v162
	ds_read_b128 v[154:157], v162 offset:1024
	ds_read_b128 v[158:161], v162 offset:2048
	ds_read_b128 v[162:165], v162 offset:3072
	ds_read_b128 v[166:169], v178
	ds_read_b128 v[170:173], v178 offset:1024
	ds_read_b128 v[174:177], v178 offset:2048
	ds_read_b128 v[178:181], v178 offset:3072
	s_add_u32 s50, s50, 0x40000
	s_addc_u32 s51, s51, 0
	s_mov_b32 m0, s58
	v_lshl_add_u64 v[222:223], s[50:51], 0, v[128:129]
	ds_read_b128 v[182:185], v153 offset:32768
	ds_read_b128 v[186:189], v153 offset:33792
	ds_read_b128 v[190:193], v153 offset:34816
	ds_read_b128 v[194:197], v153 offset:35840
	ds_read_b128 v[198:201], v153 offset:36864
	ds_read_b128 v[202:205], v153 offset:37888
	ds_read_b128 v[206:209], v153 offset:38912
	ds_read_b128 v[210:213], v153 offset:39936
	global_load_lds_dwordx4 v[222:223], off
	v_lshl_add_u64 v[222:223], s[50:51], 0, v[132:133]
	s_mov_b32 m0, s59
	s_nop 0
	global_load_lds_dwordx4 v[222:223], off
	s_waitcnt vmcnt(8) lgkmcnt(0)
	s_barrier
	v_mfma_f32_16x16x32_bf16 v[124:127], v[144:147], v[182:185], v[124:127]
	v_mfma_f32_16x16x32_bf16 v[120:123], v[158:161], v[182:185], v[120:123]
	v_mfma_f32_16x16x32_bf16 v[108:111], v[144:147], v[190:193], v[108:111]
	v_mfma_f32_16x16x32_bf16 v[104:107], v[158:161], v[190:193], v[104:107]
	v_mfma_f32_16x16x32_bf16 v[92:95], v[144:147], v[198:201], v[92:95]
	v_mfma_f32_16x16x32_bf16 v[88:91], v[158:161], v[198:201], v[88:91]
	v_mfma_f32_16x16x32_bf16 v[76:79], v[144:147], v[206:209], v[76:79]
	v_mfma_f32_16x16x32_bf16 v[72:75], v[158:161], v[206:209], v[72:75]
	v_mfma_f32_16x16x32_bf16 v[124:127], v[154:157], v[186:189], v[124:127]
	v_mfma_f32_16x16x32_bf16 v[120:123], v[162:165], v[186:189], v[120:123]
	v_mfma_f32_16x16x32_bf16 v[108:111], v[154:157], v[194:197], v[108:111]
	v_mfma_f32_16x16x32_bf16 v[104:107], v[162:165], v[194:197], v[104:107]
	v_mfma_f32_16x16x32_bf16 v[92:95], v[154:157], v[202:205], v[92:95]
	v_mfma_f32_16x16x32_bf16 v[88:91], v[162:165], v[202:205], v[88:91]
	v_mfma_f32_16x16x32_bf16 v[76:79], v[154:157], v[210:213], v[76:79]
	v_mfma_f32_16x16x32_bf16 v[72:75], v[162:165], v[210:213], v[72:75]
	v_mfma_f32_16x16x32_bf16 v[116:119], v[166:169], v[182:185], v[116:119]
	v_mfma_f32_16x16x32_bf16 v[112:115], v[174:177], v[182:185], v[112:115]
	v_mfma_f32_16x16x32_bf16 v[100:103], v[166:169], v[190:193], v[100:103]
	v_mfma_f32_16x16x32_bf16 v[96:99], v[174:177], v[190:193], v[96:99]
	v_mfma_f32_16x16x32_bf16 v[84:87], v[166:169], v[198:201], v[84:87]
	v_mfma_f32_16x16x32_bf16 v[80:83], v[174:177], v[198:201], v[80:83]
	v_mfma_f32_16x16x32_bf16 v[68:71], v[166:169], v[206:209], v[68:71]
	v_mfma_f32_16x16x32_bf16 v[64:67], v[174:177], v[206:209], v[64:67]
	v_mfma_f32_16x16x32_bf16 v[116:119], v[170:173], v[186:189], v[116:119]
	v_mfma_f32_16x16x32_bf16 v[112:115], v[178:181], v[186:189], v[112:115]
	v_mfma_f32_16x16x32_bf16 v[100:103], v[170:173], v[194:197], v[100:103]
	v_mfma_f32_16x16x32_bf16 v[96:99], v[178:181], v[194:197], v[96:99]
	v_mfma_f32_16x16x32_bf16 v[84:87], v[170:173], v[202:205], v[84:87]
	v_mfma_f32_16x16x32_bf16 v[80:83], v[178:181], v[202:205], v[80:83]
	v_mfma_f32_16x16x32_bf16 v[68:71], v[170:173], v[210:213], v[68:71]
	v_mfma_f32_16x16x32_bf16 v[64:67], v[178:181], v[210:213], v[64:67]
	s_barrier
	s_add_i32 s50, s70, s56
	v_lshl_add_u64 v[214:215], v[214:215], 0, s[22:23]
	s_mov_b32 m0, s50
	ds_read_b128 v[182:185], v153 offset:49152
	ds_read_b128 v[186:189], v153 offset:50176
	ds_read_b128 v[190:193], v153 offset:51200
	ds_read_b128 v[194:197], v153 offset:52224
	ds_read_b128 v[198:201], v153 offset:53248
	ds_read_b128 v[202:205], v153 offset:54272
	ds_read_b128 v[206:209], v153 offset:55296
	ds_read_b128 v[210:213], v153 offset:56320
	global_load_lds_dwordx4 v[214:215], off
	s_add_i32 m0, s50, 0x2000
	s_add_u32 s48, s48, 0x40080
	v_lshl_add_u64 v[214:215], v[216:217], 0, s[22:23]
	s_addc_u32 s49, s49, 0
	s_add_i32 s50, s77, s56
	global_load_lds_dwordx4 v[214:215], off
	v_lshl_add_u64 v[214:215], s[48:49], 0, v[130:131]
	s_mov_b32 m0, s50
	s_nop 0
	global_load_lds_dwordx4 v[214:215], off
	v_lshl_add_u64 v[214:215], s[48:49], 0, v[134:135]
	s_add_i32 m0, s50, 0x2000
	s_nop 0
	global_load_lds_dwordx4 v[214:215], off
	v_lshl_add_u64 v[214:215], v[218:219], 0, s[22:23]
	s_mov_b32 m0, s63
	s_nop 0
	global_load_lds_dwordx4 v[214:215], off
	v_lshl_add_u64 v[214:215], v[220:221], 0, s[22:23]
	s_mov_b32 m0, s64
	s_nop 0
	global_load_lds_dwordx4 v[214:215], off
	s_waitcnt vmcnt(8) lgkmcnt(0)
	s_barrier
	v_mfma_f32_16x16x32_bf16 v[60:63], v[144:147], v[182:185], v[60:63]
	v_mfma_f32_16x16x32_bf16 v[56:59], v[158:161], v[182:185], v[56:59]
	v_mfma_f32_16x16x32_bf16 v[44:47], v[144:147], v[190:193], v[44:47]
	v_mfma_f32_16x16x32_bf16 v[40:43], v[158:161], v[190:193], v[40:43]
	v_mfma_f32_16x16x32_bf16 v[28:31], v[144:147], v[198:201], v[28:31]
	v_mfma_f32_16x16x32_bf16 v[24:27], v[158:161], v[198:201], v[24:27]
	v_mfma_f32_16x16x32_bf16 v[12:15], v[144:147], v[206:209], v[12:15]
	v_mfma_f32_16x16x32_bf16 v[8:11], v[158:161], v[206:209], v[8:11]
	v_mfma_f32_16x16x32_bf16 v[60:63], v[154:157], v[186:189], v[60:63]
	v_mfma_f32_16x16x32_bf16 v[56:59], v[162:165], v[186:189], v[56:59]
	v_mfma_f32_16x16x32_bf16 v[44:47], v[154:157], v[194:197], v[44:47]
	v_mfma_f32_16x16x32_bf16 v[40:43], v[162:165], v[194:197], v[40:43]
	v_mfma_f32_16x16x32_bf16 v[28:31], v[154:157], v[202:205], v[28:31]
	v_mfma_f32_16x16x32_bf16 v[24:27], v[162:165], v[202:205], v[24:27]
	v_mfma_f32_16x16x32_bf16 v[12:15], v[154:157], v[210:213], v[12:15]
	v_mfma_f32_16x16x32_bf16 v[8:11], v[162:165], v[210:213], v[8:11]
	v_mfma_f32_16x16x32_bf16 v[52:55], v[166:169], v[182:185], v[52:55]
	v_mfma_f32_16x16x32_bf16 v[48:51], v[174:177], v[182:185], v[48:51]
	v_mfma_f32_16x16x32_bf16 v[36:39], v[166:169], v[190:193], v[36:39]
	v_mfma_f32_16x16x32_bf16 v[32:35], v[174:177], v[190:193], v[32:35]
	v_mfma_f32_16x16x32_bf16 v[20:23], v[166:169], v[198:201], v[20:23]
	v_mfma_f32_16x16x32_bf16 v[16:19], v[174:177], v[198:201], v[16:19]
	v_mfma_f32_16x16x32_bf16 v[4:7], v[166:169], v[206:209], v[4:7]
	v_mfma_f32_16x16x32_bf16 v[0:3], v[174:177], v[206:209], v[0:3]
	v_mfma_f32_16x16x32_bf16 v[52:55], v[170:173], v[186:189], v[52:55]
	v_mfma_f32_16x16x32_bf16 v[48:51], v[178:181], v[186:189], v[48:51]
	v_mfma_f32_16x16x32_bf16 v[36:39], v[170:173], v[194:197], v[36:39]
	v_mfma_f32_16x16x32_bf16 v[32:35], v[178:181], v[194:197], v[32:35]
	v_mfma_f32_16x16x32_bf16 v[20:23], v[170:173], v[202:205], v[20:23]
	v_mfma_f32_16x16x32_bf16 v[16:19], v[178:181], v[202:205], v[16:19]
	v_mfma_f32_16x16x32_bf16 v[4:7], v[170:173], v[210:213], v[4:7]
	v_mfma_f32_16x16x32_bf16 v[0:3], v[178:181], v[210:213], v[0:3]
	s_barrier
	s_add_i32 s71, s71, 2
	s_add_u32 s68, s68, 0x100
	s_addc_u32 s69, s69, 0
	s_add_u32 s46, s46, 0x100
	s_addc_u32 s47, s47, 0
	s_cmp_gt_u32 s71, 13
	s_cbranch_scc0 .LBB0_1603
	s_and_b64 vcc, exec, s[36:37]
	s_cbranch_vccz .LBB0_1606
	s_barrier

.LBB0_1719:
	ds_read_b128 v[146:149], v226
	ds_read_b128 v[150:153], v226 offset:1024
	ds_read_b128 v[154:157], v226 offset:2048
	ds_read_b128 v[158:161], v226 offset:3072
	ds_read_b128 v[162:165], v227
	ds_read_b128 v[166:169], v227 offset:1024
	ds_read_b128 v[170:173], v227 offset:2048
	ds_read_b128 v[174:177], v227 offset:3072
	s_add_u32 s52, s10, 0xfffc2080
	s_addc_u32 s53, s11, -1
	s_cmp_eq_u32 s82, 12
	s_cselect_b32 s55, s49, s53
	s_cselect_b32 s54, s48, s52
	s_cselect_b32 s53, s27, s81
	s_cselect_b32 s52, s47, s71
	v_lshl_add_u64 v[210:211], s[10:11], 0, v[138:139]
	s_add_i32 m0, s59, 0xc000
	ds_read_b128 v[178:181], v228
	ds_read_b128 v[182:185], v228 offset:1024
	ds_read_b128 v[186:189], v228 offset:2048
	ds_read_b128 v[190:193], v228 offset:3072
	ds_read_b128 v[194:197], v228 offset:4096
	ds_read_b128 v[198:201], v228 offset:5120
	ds_read_b128 v[202:205], v228 offset:6144
	ds_read_b128 v[206:209], v228 offset:7168
	global_load_lds_dwordx4 v[210:211], off
	v_lshl_add_u64 v[210:211], s[10:11], 0, v[136:137]
	s_add_i32 m0, s59, 0xe000
	s_nop 0
	global_load_lds_dwordx4 v[210:211], off
	s_waitcnt vmcnt(8) lgkmcnt(0)
	s_barrier
	v_mfma_f32_16x16x32_bf16 v[124:127], v[146:149], v[178:181], v[124:127]
	v_mfma_f32_16x16x32_bf16 v[120:123], v[154:157], v[178:181], v[120:123]
	v_mfma_f32_16x16x32_bf16 v[116:119], v[146:149], v[186:189], v[116:119]
	v_mfma_f32_16x16x32_bf16 v[108:111], v[154:157], v[186:189], v[108:111]
	v_mfma_f32_16x16x32_bf16 v[100:103], v[146:149], v[194:197], v[100:103]
	v_mfma_f32_16x16x32_bf16 v[96:99], v[154:157], v[194:197], v[96:99]
	v_mfma_f32_16x16x32_bf16 v[84:87], v[146:149], v[202:205], v[84:87]
	v_mfma_f32_16x16x32_bf16 v[76:79], v[154:157], v[202:205], v[76:79]
	v_mfma_f32_16x16x32_bf16 v[124:127], v[150:153], v[182:185], v[124:127]
	v_mfma_f32_16x16x32_bf16 v[120:123], v[158:161], v[182:185], v[120:123]
	v_mfma_f32_16x16x32_bf16 v[116:119], v[150:153], v[190:193], v[116:119]
	v_mfma_f32_16x16x32_bf16 v[108:111], v[158:161], v[190:193], v[108:111]
	v_mfma_f32_16x16x32_bf16 v[100:103], v[150:153], v[198:201], v[100:103]
	v_mfma_f32_16x16x32_bf16 v[96:99], v[158:161], v[198:201], v[96:99]
	v_mfma_f32_16x16x32_bf16 v[84:87], v[150:153], v[206:209], v[84:87]
	v_mfma_f32_16x16x32_bf16 v[76:79], v[158:161], v[206:209], v[76:79]
	v_mfma_f32_16x16x32_bf16 v[112:115], v[162:165], v[178:181], v[112:115]
	v_mfma_f32_16x16x32_bf16 v[104:107], v[170:173], v[178:181], v[104:107]
	v_mfma_f32_16x16x32_bf16 v[92:95], v[162:165], v[186:189], v[92:95]
	v_mfma_f32_16x16x32_bf16 v[88:91], v[170:173], v[186:189], v[88:91]
	v_mfma_f32_16x16x32_bf16 v[80:83], v[162:165], v[194:197], v[80:83]
	v_mfma_f32_16x16x32_bf16 v[72:75], v[170:173], v[194:197], v[72:75]
	v_mfma_f32_16x16x32_bf16 v[68:71], v[162:165], v[202:205], v[68:71]
	v_mfma_f32_16x16x32_bf16 v[64:67], v[170:173], v[202:205], v[64:67]
	v_mfma_f32_16x16x32_bf16 v[112:115], v[166:169], v[182:185], v[112:115]
	v_mfma_f32_16x16x32_bf16 v[104:107], v[174:177], v[182:185], v[104:107]
	v_mfma_f32_16x16x32_bf16 v[92:95], v[166:169], v[190:193], v[92:95]
	v_mfma_f32_16x16x32_bf16 v[88:91], v[174:177], v[190:193], v[88:91]
	v_mfma_f32_16x16x32_bf16 v[80:83], v[166:169], v[198:201], v[80:83]
	v_mfma_f32_16x16x32_bf16 v[72:75], v[174:177], v[198:201], v[72:75]
	v_mfma_f32_16x16x32_bf16 v[68:71], v[166:169], v[206:209], v[68:71]
	v_mfma_f32_16x16x32_bf16 v[64:67], v[174:177], v[206:209], v[64:67]
	s_barrier
	s_add_i32 s70, s69, s43
	v_lshl_add_u64 v[210:211], s[52:53], 0, v[130:131]
	s_mov_b32 m0, s70
	ds_read_b128 v[178:181], v228 offset:16384
	ds_read_b128 v[182:185], v228 offset:17408
	ds_read_b128 v[186:189], v228 offset:18432
	ds_read_b128 v[190:193], v228 offset:19456
	ds_read_b128 v[194:197], v228 offset:20480
	ds_read_b128 v[198:201], v228 offset:21504
	ds_read_b128 v[202:205], v228 offset:22528
	ds_read_b128 v[206:209], v228 offset:23552
	global_load_lds_dwordx4 v[210:211], off
	s_add_i32 m0, s70, 0x2000
	s_add_u32 s84, s52, 0x40000
	v_lshl_add_u64 v[212:213], s[52:53], 0, v[134:135]
	s_addc_u32 s85, s53, 0
	s_add_i32 s70, s75, s43
	global_load_lds_dwordx4 v[212:213], off
	v_lshl_add_u64 v[214:215], s[84:85], 0, v[130:131]
	s_mov_b32 m0, s70
	v_lshl_add_u64 v[216:217], s[54:55], 0, v[132:133]
	global_load_lds_dwordx4 v[214:215], off
	v_lshl_add_u64 v[214:215], s[84:85], 0, v[134:135]
	s_add_i32 m0, s70, 0x2000
	s_nop 0
	global_load_lds_dwordx4 v[214:215], off
	v_lshl_add_u64 v[214:215], s[54:55], 0, v[128:129]
	s_mov_b32 m0, s59
	s_nop 0
	global_load_lds_dwordx4 v[214:215], off
	s_mov_b32 m0, s60
	s_nop 0
	global_load_lds_dwordx4 v[216:217], off
	s_waitcnt vmcnt(8) lgkmcnt(0)
	s_barrier
	v_mfma_f32_16x16x32_bf16 v[60:63], v[146:149], v[178:181], v[60:63]
	v_mfma_f32_16x16x32_bf16 v[56:59], v[154:157], v[178:181], v[56:59]
	v_mfma_f32_16x16x32_bf16 v[52:55], v[146:149], v[186:189], v[52:55]
	v_mfma_f32_16x16x32_bf16 v[44:47], v[154:157], v[186:189], v[44:47]
	v_mfma_f32_16x16x32_bf16 v[36:39], v[146:149], v[194:197], v[36:39]
	v_mfma_f32_16x16x32_bf16 v[32:35], v[154:157], v[194:197], v[32:35]
	v_mfma_f32_16x16x32_bf16 v[20:23], v[146:149], v[202:205], v[20:23]
	v_mfma_f32_16x16x32_bf16 v[12:15], v[154:157], v[202:205], v[12:15]
	v_mfma_f32_16x16x32_bf16 v[60:63], v[150:153], v[182:185], v[60:63]
	v_mfma_f32_16x16x32_bf16 v[56:59], v[158:161], v[182:185], v[56:59]
	v_mfma_f32_16x16x32_bf16 v[52:55], v[150:153], v[190:193], v[52:55]
	v_mfma_f32_16x16x32_bf16 v[44:47], v[158:161], v[190:193], v[44:47]
	v_mfma_f32_16x16x32_bf16 v[36:39], v[150:153], v[198:201], v[36:39]
	v_mfma_f32_16x16x32_bf16 v[32:35], v[158:161], v[198:201], v[32:35]
	v_mfma_f32_16x16x32_bf16 v[20:23], v[150:153], v[206:209], v[20:23]
	v_mfma_f32_16x16x32_bf16 v[12:15], v[158:161], v[206:209], v[12:15]
	v_mfma_f32_16x16x32_bf16 v[48:51], v[162:165], v[178:181], v[48:51]
	v_mfma_f32_16x16x32_bf16 v[40:43], v[170:173], v[178:181], v[40:43]
	v_mfma_f32_16x16x32_bf16 v[28:31], v[162:165], v[186:189], v[28:31]
	v_mfma_f32_16x16x32_bf16 v[24:27], v[170:173], v[186:189], v[24:27]
	v_mfma_f32_16x16x32_bf16 v[16:19], v[162:165], v[194:197], v[16:19]
	v_mfma_f32_16x16x32_bf16 v[8:11], v[170:173], v[194:197], v[8:11]
	v_mfma_f32_16x16x32_bf16 v[4:7], v[162:165], v[202:205], v[4:7]
	v_mfma_f32_16x16x32_bf16 v[0:3], v[170:173], v[202:205], v[0:3]
	v_mfma_f32_16x16x32_bf16 v[48:51], v[166:169], v[182:185], v[48:51]
	v_mfma_f32_16x16x32_bf16 v[40:43], v[174:177], v[182:185], v[40:43]
	v_mfma_f32_16x16x32_bf16 v[28:31], v[166:169], v[190:193], v[28:31]
	v_mfma_f32_16x16x32_bf16 v[24:27], v[174:177], v[190:193], v[24:27]
	v_mfma_f32_16x16x32_bf16 v[16:19], v[166:169], v[198:201], v[16:19]
	v_mfma_f32_16x16x32_bf16 v[8:11], v[174:177], v[198:201], v[8:11]
	v_mfma_f32_16x16x32_bf16 v[4:7], v[166:169], v[206:209], v[4:7]
	v_mfma_f32_16x16x32_bf16 v[0:3], v[174:177], v[206:209], v[0:3]
	s_barrier
	s_add_i32 s70, 0, 0x18000
	s_add_i32 s83, 0, 0x1c000
	v_add_u32_e32 v158, s70, v225
	v_add_u32_e32 v174, s83, v225
	ds_read_b128 v[146:149], v158
	ds_read_b128 v[150:153], v158 offset:1024
	ds_read_b128 v[154:157], v158 offset:2048
	ds_read_b128 v[158:161], v158 offset:3072
	ds_read_b128 v[162:165], v174
	ds_read_b128 v[166:169], v174 offset:1024
	ds_read_b128 v[170:173], v174 offset:2048
	ds_read_b128 v[174:177], v174 offset:3072
	s_add_u32 s54, s54, 0x3e000
	s_addc_u32 s55, s55, 0
	s_mov_b32 m0, s61
	v_lshl_add_u64 v[218:219], s[54:55], 0, v[128:129]
	ds_read_b128 v[178:181], v228 offset:32768
	ds_read_b128 v[182:185], v228 offset:33792
	ds_read_b128 v[186:189], v228 offset:34816
	ds_read_b128 v[190:193], v228 offset:35840
	ds_read_b128 v[194:197], v228 offset:36864
	ds_read_b128 v[198:201], v228 offset:37888
	ds_read_b128 v[202:205], v228 offset:38912
	ds_read_b128 v[206:209], v228 offset:39936
	global_load_lds_dwordx4 v[218:219], off
	v_lshl_add_u64 v[218:219], s[54:55], 0, v[132:133]
	s_mov_b32 m0, s62
	s_nop 0
	global_load_lds_dwordx4 v[218:219], off
	s_waitcnt vmcnt(8) lgkmcnt(0)
	s_barrier
	v_mfma_f32_16x16x32_bf16 v[124:127], v[146:149], v[178:181], v[124:127]
	v_mfma_f32_16x16x32_bf16 v[120:123], v[154:157], v[178:181], v[120:123]
	v_mfma_f32_16x16x32_bf16 v[116:119], v[146:149], v[186:189], v[116:119]
	v_mfma_f32_16x16x32_bf16 v[108:111], v[154:157], v[186:189], v[108:111]
	v_mfma_f32_16x16x32_bf16 v[100:103], v[146:149], v[194:197], v[100:103]
	v_mfma_f32_16x16x32_bf16 v[96:99], v[154:157], v[194:197], v[96:99]
	v_mfma_f32_16x16x32_bf16 v[84:87], v[146:149], v[202:205], v[84:87]
	v_mfma_f32_16x16x32_bf16 v[76:79], v[154:157], v[202:205], v[76:79]
	v_mfma_f32_16x16x32_bf16 v[124:127], v[150:153], v[182:185], v[124:127]
	v_mfma_f32_16x16x32_bf16 v[120:123], v[158:161], v[182:185], v[120:123]
	v_mfma_f32_16x16x32_bf16 v[116:119], v[150:153], v[190:193], v[116:119]
	v_mfma_f32_16x16x32_bf16 v[108:111], v[158:161], v[190:193], v[108:111]
	v_mfma_f32_16x16x32_bf16 v[100:103], v[150:153], v[198:201], v[100:103]
	v_mfma_f32_16x16x32_bf16 v[96:99], v[158:161], v[198:201], v[96:99]
	v_mfma_f32_16x16x32_bf16 v[84:87], v[150:153], v[206:209], v[84:87]
	v_mfma_f32_16x16x32_bf16 v[76:79], v[158:161], v[206:209], v[76:79]
	v_mfma_f32_16x16x32_bf16 v[112:115], v[162:165], v[178:181], v[112:115]
	v_mfma_f32_16x16x32_bf16 v[104:107], v[170:173], v[178:181], v[104:107]
	v_mfma_f32_16x16x32_bf16 v[92:95], v[162:165], v[186:189], v[92:95]
	v_mfma_f32_16x16x32_bf16 v[88:91], v[170:173], v[186:189], v[88:91]
	v_mfma_f32_16x16x32_bf16 v[80:83], v[162:165], v[194:197], v[80:83]
	v_mfma_f32_16x16x32_bf16 v[72:75], v[170:173], v[194:197], v[72:75]
	v_mfma_f32_16x16x32_bf16 v[68:71], v[162:165], v[202:205], v[68:71]
	v_mfma_f32_16x16x32_bf16 v[64:67], v[170:173], v[202:205], v[64:67]
	v_mfma_f32_16x16x32_bf16 v[112:115], v[166:169], v[182:185], v[112:115]
	v_mfma_f32_16x16x32_bf16 v[104:107], v[174:177], v[182:185], v[104:107]
	v_mfma_f32_16x16x32_bf16 v[92:95], v[166:169], v[190:193], v[92:95]
	v_mfma_f32_16x16x32_bf16 v[88:91], v[174:177], v[190:193], v[88:91]
	v_mfma_f32_16x16x32_bf16 v[80:83], v[166:169], v[198:201], v[80:83]
	v_mfma_f32_16x16x32_bf16 v[72:75], v[174:177], v[198:201], v[72:75]
	v_mfma_f32_16x16x32_bf16 v[68:71], v[166:169], v[206:209], v[68:71]
	v_mfma_f32_16x16x32_bf16 v[64:67], v[174:177], v[206:209], v[64:67]
	s_barrier
	s_add_i32 s54, s70, s43
	v_lshl_add_u64 v[210:211], v[210:211], 0, s[36:37]
	s_mov_b32 m0, s54
	ds_read_b128 v[178:181], v228 offset:49152
	ds_read_b128 v[182:185], v228 offset:50176
	ds_read_b128 v[186:189], v228 offset:51200
	ds_read_b128 v[190:193], v228 offset:52224
	ds_read_b128 v[194:197], v228 offset:53248
	ds_read_b128 v[198:201], v228 offset:54272
	ds_read_b128 v[202:205], v228 offset:55296
	ds_read_b128 v[206:209], v228 offset:56320
	global_load_lds_dwordx4 v[210:211], off
	s_add_i32 m0, s54, 0x2000
	s_add_u32 s52, s52, 0x40080
	v_lshl_add_u64 v[210:211], v[212:213], 0, s[36:37]
	s_addc_u32 s53, s53, 0
	s_add_i32 s54, s83, s43
	global_load_lds_dwordx4 v[210:211], off
	v_lshl_add_u64 v[210:211], s[52:53], 0, v[130:131]
	s_mov_b32 m0, s54
	s_nop 0
	global_load_lds_dwordx4 v[210:211], off
	v_lshl_add_u64 v[210:211], s[52:53], 0, v[134:135]
	s_add_i32 m0, s54, 0x2000
	s_nop 0
	global_load_lds_dwordx4 v[210:211], off
	v_lshl_add_u64 v[210:211], v[214:215], 0, s[36:37]
	s_mov_b32 m0, s64
	s_nop 0
	global_load_lds_dwordx4 v[210:211], off
	v_lshl_add_u64 v[210:211], v[216:217], 0, s[36:37]
	s_mov_b32 m0, s65
	s_nop 0
	global_load_lds_dwordx4 v[210:211], off
	s_waitcnt vmcnt(8) lgkmcnt(0)
	s_barrier
	v_mfma_f32_16x16x32_bf16 v[60:63], v[146:149], v[178:181], v[60:63]
	v_mfma_f32_16x16x32_bf16 v[56:59], v[154:157], v[178:181], v[56:59]
	v_mfma_f32_16x16x32_bf16 v[52:55], v[146:149], v[186:189], v[52:55]
	v_mfma_f32_16x16x32_bf16 v[44:47], v[154:157], v[186:189], v[44:47]
	v_mfma_f32_16x16x32_bf16 v[36:39], v[146:149], v[194:197], v[36:39]
	v_mfma_f32_16x16x32_bf16 v[32:35], v[154:157], v[194:197], v[32:35]
	v_mfma_f32_16x16x32_bf16 v[20:23], v[146:149], v[202:205], v[20:23]
	v_mfma_f32_16x16x32_bf16 v[12:15], v[154:157], v[202:205], v[12:15]
	v_mfma_f32_16x16x32_bf16 v[60:63], v[150:153], v[182:185], v[60:63]
	v_mfma_f32_16x16x32_bf16 v[56:59], v[158:161], v[182:185], v[56:59]
	v_mfma_f32_16x16x32_bf16 v[52:55], v[150:153], v[190:193], v[52:55]
	v_mfma_f32_16x16x32_bf16 v[44:47], v[158:161], v[190:193], v[44:47]
	v_mfma_f32_16x16x32_bf16 v[36:39], v[150:153], v[198:201], v[36:39]
	v_mfma_f32_16x16x32_bf16 v[32:35], v[158:161], v[198:201], v[32:35]
	v_mfma_f32_16x16x32_bf16 v[20:23], v[150:153], v[206:209], v[20:23]
	v_mfma_f32_16x16x32_bf16 v[12:15], v[158:161], v[206:209], v[12:15]
	v_mfma_f32_16x16x32_bf16 v[48:51], v[162:165], v[178:181], v[48:51]
	v_mfma_f32_16x16x32_bf16 v[40:43], v[170:173], v[178:181], v[40:43]
	v_mfma_f32_16x16x32_bf16 v[28:31], v[162:165], v[186:189], v[28:31]
	v_mfma_f32_16x16x32_bf16 v[24:27], v[170:173], v[186:189], v[24:27]
	v_mfma_f32_16x16x32_bf16 v[16:19], v[162:165], v[194:197], v[16:19]
	v_mfma_f32_16x16x32_bf16 v[8:11], v[170:173], v[194:197], v[8:11]
	v_mfma_f32_16x16x32_bf16 v[4:7], v[162:165], v[202:205], v[4:7]
	v_mfma_f32_16x16x32_bf16 v[0:3], v[170:173], v[202:205], v[0:3]
	v_mfma_f32_16x16x32_bf16 v[48:51], v[166:169], v[182:185], v[48:51]
	v_mfma_f32_16x16x32_bf16 v[40:43], v[174:177], v[182:185], v[40:43]
	v_mfma_f32_16x16x32_bf16 v[28:31], v[166:169], v[190:193], v[28:31]
	v_mfma_f32_16x16x32_bf16 v[24:27], v[174:177], v[190:193], v[24:27]
	v_mfma_f32_16x16x32_bf16 v[16:19], v[166:169], v[198:201], v[16:19]
	v_mfma_f32_16x16x32_bf16 v[8:11], v[174:177], v[198:201], v[8:11]
	v_mfma_f32_16x16x32_bf16 v[4:7], v[166:169], v[206:209], v[4:7]
	v_mfma_f32_16x16x32_bf16 v[0:3], v[174:177], v[206:209], v[0:3]
	s_barrier
	s_add_i32 s82, s82, 2
	s_add_u32 s71, s71, 0x100
	s_addc_u32 s81, s81, 0
	s_add_u32 s10, s10, 0x100
	s_addc_u32 s11, s11, 0
	s_cmp_gt_u32 s82, 13
	s_cbranch_scc0 .LBB0_1719
	s_and_b64 vcc, exec, s[38:39]
	s_cbranch_vccz .LBB0_1722
	s_barrier

.LBB0_1835:
	ds_read_b128 v[144:147], v151
	ds_read_b128 v[154:157], v151 offset:1024
	ds_read_b128 v[158:161], v151 offset:2048
	ds_read_b128 v[162:165], v151 offset:3072
	ds_read_b128 v[166:169], v152
	ds_read_b128 v[170:173], v152 offset:1024
	ds_read_b128 v[174:177], v152 offset:2048
	ds_read_b128 v[178:181], v152 offset:3072
	s_add_u32 s40, s38, 0x100
	s_addc_u32 s41, s39, 0
	s_cmp_eq_u32 s62, 40
	s_cselect_b32 s45, s11, s41
	s_cselect_b32 s44, s10, s40
	s_cselect_b32 s43, s37, s27
	s_cselect_b32 s42, s36, s26
	v_lshl_add_u64 v[214:215], s[38:39], 0, v[138:139]
	s_add_i32 m0, s48, 0xc000
	ds_read_b128 v[182:185], v153
	ds_read_b128 v[186:189], v153 offset:1024
	ds_read_b128 v[190:193], v153 offset:2048
	ds_read_b128 v[194:197], v153 offset:3072
	ds_read_b128 v[198:201], v153 offset:4096
	ds_read_b128 v[202:205], v153 offset:5120
	ds_read_b128 v[206:209], v153 offset:6144
	ds_read_b128 v[210:213], v153 offset:7168
	global_load_lds_dwordx4 v[214:215], off
	v_lshl_add_u64 v[214:215], s[38:39], 0, v[136:137]
	s_add_i32 m0, s48, 0xe000
	s_nop 0
	global_load_lds_dwordx4 v[214:215], off
	s_waitcnt vmcnt(8) lgkmcnt(0)
	s_barrier
	v_mfma_f32_16x16x32_bf16 v[124:127], v[144:147], v[182:185], v[124:127]
	v_mfma_f32_16x16x32_bf16 v[120:123], v[158:161], v[182:185], v[120:123]
	v_mfma_f32_16x16x32_bf16 v[108:111], v[144:147], v[190:193], v[108:111]
	v_mfma_f32_16x16x32_bf16 v[104:107], v[158:161], v[190:193], v[104:107]
	v_mfma_f32_16x16x32_bf16 v[92:95], v[144:147], v[198:201], v[92:95]
	v_mfma_f32_16x16x32_bf16 v[88:91], v[158:161], v[198:201], v[88:91]
	v_mfma_f32_16x16x32_bf16 v[76:79], v[144:147], v[206:209], v[76:79]
	v_mfma_f32_16x16x32_bf16 v[72:75], v[158:161], v[206:209], v[72:75]
	v_mfma_f32_16x16x32_bf16 v[124:127], v[154:157], v[186:189], v[124:127]
	v_mfma_f32_16x16x32_bf16 v[120:123], v[162:165], v[186:189], v[120:123]
	v_mfma_f32_16x16x32_bf16 v[108:111], v[154:157], v[194:197], v[108:111]
	v_mfma_f32_16x16x32_bf16 v[104:107], v[162:165], v[194:197], v[104:107]
	v_mfma_f32_16x16x32_bf16 v[92:95], v[154:157], v[202:205], v[92:95]
	v_mfma_f32_16x16x32_bf16 v[88:91], v[162:165], v[202:205], v[88:91]
	v_mfma_f32_16x16x32_bf16 v[76:79], v[154:157], v[210:213], v[76:79]
	v_mfma_f32_16x16x32_bf16 v[72:75], v[162:165], v[210:213], v[72:75]
	v_mfma_f32_16x16x32_bf16 v[116:119], v[166:169], v[182:185], v[116:119]
	v_mfma_f32_16x16x32_bf16 v[112:115], v[174:177], v[182:185], v[112:115]
	v_mfma_f32_16x16x32_bf16 v[100:103], v[166:169], v[190:193], v[100:103]
	v_mfma_f32_16x16x32_bf16 v[96:99], v[174:177], v[190:193], v[96:99]
	v_mfma_f32_16x16x32_bf16 v[84:87], v[166:169], v[198:201], v[84:87]
	v_mfma_f32_16x16x32_bf16 v[80:83], v[174:177], v[198:201], v[80:83]
	v_mfma_f32_16x16x32_bf16 v[68:71], v[166:169], v[206:209], v[68:71]
	v_mfma_f32_16x16x32_bf16 v[64:67], v[174:177], v[206:209], v[64:67]
	v_mfma_f32_16x16x32_bf16 v[116:119], v[170:173], v[186:189], v[116:119]
	v_mfma_f32_16x16x32_bf16 v[112:115], v[178:181], v[186:189], v[112:115]
	v_mfma_f32_16x16x32_bf16 v[100:103], v[170:173], v[194:197], v[100:103]
	v_mfma_f32_16x16x32_bf16 v[96:99], v[178:181], v[194:197], v[96:99]
	v_mfma_f32_16x16x32_bf16 v[84:87], v[170:173], v[202:205], v[84:87]
	v_mfma_f32_16x16x32_bf16 v[80:83], v[178:181], v[202:205], v[80:83]
	v_mfma_f32_16x16x32_bf16 v[68:71], v[170:173], v[210:213], v[68:71]
	v_mfma_f32_16x16x32_bf16 v[64:67], v[178:181], v[210:213], v[64:67]
	s_barrier
	s_add_i32 s38, s57, s47
	v_lshl_add_u64 v[214:215], s[42:43], 0, v[130:131]
	s_mov_b32 m0, s38
	ds_read_b128 v[182:185], v153 offset:16384
	ds_read_b128 v[186:189], v153 offset:17408
	ds_read_b128 v[190:193], v153 offset:18432
	ds_read_b128 v[194:197], v153 offset:19456
	ds_read_b128 v[198:201], v153 offset:20480
	ds_read_b128 v[202:205], v153 offset:21504
	ds_read_b128 v[206:209], v153 offset:22528
	ds_read_b128 v[210:213], v153 offset:23552
	global_load_lds_dwordx4 v[214:215], off
	s_add_i32 m0, s38, 0x2000
	s_add_u32 s38, s42, 0xb0000
	v_lshl_add_u64 v[216:217], s[42:43], 0, v[134:135]
	s_addc_u32 s39, s43, 0
	s_add_i32 s63, s58, s47
	global_load_lds_dwordx4 v[216:217], off
	v_lshl_add_u64 v[218:219], s[38:39], 0, v[130:131]
	s_mov_b32 m0, s63
	v_lshl_add_u64 v[220:221], s[44:45], 0, v[132:133]
	global_load_lds_dwordx4 v[218:219], off
	v_lshl_add_u64 v[218:219], s[38:39], 0, v[134:135]
	s_add_i32 m0, s63, 0x2000
	s_nop 0
	global_load_lds_dwordx4 v[218:219], off
	v_lshl_add_u64 v[218:219], s[44:45], 0, v[128:129]
	s_mov_b32 m0, s48
	s_nop 0
	global_load_lds_dwordx4 v[218:219], off
	s_mov_b32 m0, s49
	s_nop 0
	global_load_lds_dwordx4 v[220:221], off
	s_waitcnt vmcnt(8) lgkmcnt(0)
	s_barrier
	v_mfma_f32_16x16x32_bf16 v[60:63], v[144:147], v[182:185], v[60:63]
	v_mfma_f32_16x16x32_bf16 v[56:59], v[158:161], v[182:185], v[56:59]
	v_mfma_f32_16x16x32_bf16 v[44:47], v[144:147], v[190:193], v[44:47]
	v_mfma_f32_16x16x32_bf16 v[40:43], v[158:161], v[190:193], v[40:43]
	v_mfma_f32_16x16x32_bf16 v[28:31], v[144:147], v[198:201], v[28:31]
	v_mfma_f32_16x16x32_bf16 v[24:27], v[158:161], v[198:201], v[24:27]
	v_mfma_f32_16x16x32_bf16 v[12:15], v[144:147], v[206:209], v[12:15]
	v_mfma_f32_16x16x32_bf16 v[8:11], v[158:161], v[206:209], v[8:11]
	v_mfma_f32_16x16x32_bf16 v[60:63], v[154:157], v[186:189], v[60:63]
	v_mfma_f32_16x16x32_bf16 v[56:59], v[162:165], v[186:189], v[56:59]
	v_mfma_f32_16x16x32_bf16 v[44:47], v[154:157], v[194:197], v[44:47]
	v_mfma_f32_16x16x32_bf16 v[40:43], v[162:165], v[194:197], v[40:43]
	v_mfma_f32_16x16x32_bf16 v[28:31], v[154:157], v[202:205], v[28:31]
	v_mfma_f32_16x16x32_bf16 v[24:27], v[162:165], v[202:205], v[24:27]
	v_mfma_f32_16x16x32_bf16 v[12:15], v[154:157], v[210:213], v[12:15]
	v_mfma_f32_16x16x32_bf16 v[8:11], v[162:165], v[210:213], v[8:11]
	v_mfma_f32_16x16x32_bf16 v[52:55], v[166:169], v[182:185], v[52:55]
	v_mfma_f32_16x16x32_bf16 v[48:51], v[174:177], v[182:185], v[48:51]
	v_mfma_f32_16x16x32_bf16 v[36:39], v[166:169], v[190:193], v[36:39]
	v_mfma_f32_16x16x32_bf16 v[32:35], v[174:177], v[190:193], v[32:35]
	v_mfma_f32_16x16x32_bf16 v[20:23], v[166:169], v[198:201], v[20:23]
	v_mfma_f32_16x16x32_bf16 v[16:19], v[174:177], v[198:201], v[16:19]
	v_mfma_f32_16x16x32_bf16 v[4:7], v[166:169], v[206:209], v[4:7]
	v_mfma_f32_16x16x32_bf16 v[0:3], v[174:177], v[206:209], v[0:3]
	v_mfma_f32_16x16x32_bf16 v[52:55], v[170:173], v[186:189], v[52:55]
	v_mfma_f32_16x16x32_bf16 v[48:51], v[178:181], v[186:189], v[48:51]
	v_mfma_f32_16x16x32_bf16 v[36:39], v[170:173], v[194:197], v[36:39]
	v_mfma_f32_16x16x32_bf16 v[32:35], v[178:181], v[194:197], v[32:35]
	v_mfma_f32_16x16x32_bf16 v[20:23], v[170:173], v[202:205], v[20:23]
	v_mfma_f32_16x16x32_bf16 v[16:19], v[178:181], v[202:205], v[16:19]
	v_mfma_f32_16x16x32_bf16 v[4:7], v[170:173], v[210:213], v[4:7]
	v_mfma_f32_16x16x32_bf16 v[0:3], v[178:181], v[210:213], v[0:3]
	s_barrier
	s_add_i32 s63, 0, 0x18000
	s_add_i32 s64, 0, 0x1c000
	v_add_u32_e32 v162, s63, v150
	v_add_u32_e32 v178, s64, v150
	ds_read_b128 v[144:147], v162
	ds_read_b128 v[154:157], v162 offset:1024
	ds_read_b128 v[158:161], v162 offset:2048
	ds_read_b128 v[162:165], v162 offset:3072
	ds_read_b128 v[166:169], v178
	ds_read_b128 v[170:173], v178 offset:1024
	ds_read_b128 v[174:177], v178 offset:2048
	ds_read_b128 v[178:181], v178 offset:3072
	s_add_u32 s38, s44, 0xb0000
	s_addc_u32 s39, s45, 0
	s_mov_b32 m0, s50
	v_lshl_add_u64 v[222:223], s[38:39], 0, v[128:129]
	ds_read_b128 v[182:185], v153 offset:32768
	ds_read_b128 v[186:189], v153 offset:33792
	ds_read_b128 v[190:193], v153 offset:34816
	ds_read_b128 v[194:197], v153 offset:35840
	ds_read_b128 v[198:201], v153 offset:36864
	ds_read_b128 v[202:205], v153 offset:37888
	ds_read_b128 v[206:209], v153 offset:38912
	ds_read_b128 v[210:213], v153 offset:39936
	global_load_lds_dwordx4 v[222:223], off
	v_lshl_add_u64 v[222:223], s[38:39], 0, v[132:133]
	s_mov_b32 m0, s51
	s_nop 0
	global_load_lds_dwordx4 v[222:223], off
	s_waitcnt vmcnt(8) lgkmcnt(0)
	s_barrier
	v_mfma_f32_16x16x32_bf16 v[124:127], v[144:147], v[182:185], v[124:127]
	v_mfma_f32_16x16x32_bf16 v[120:123], v[158:161], v[182:185], v[120:123]
	v_mfma_f32_16x16x32_bf16 v[108:111], v[144:147], v[190:193], v[108:111]
	v_mfma_f32_16x16x32_bf16 v[104:107], v[158:161], v[190:193], v[104:107]
	v_mfma_f32_16x16x32_bf16 v[92:95], v[144:147], v[198:201], v[92:95]
	v_mfma_f32_16x16x32_bf16 v[88:91], v[158:161], v[198:201], v[88:91]
	v_mfma_f32_16x16x32_bf16 v[76:79], v[144:147], v[206:209], v[76:79]
	v_mfma_f32_16x16x32_bf16 v[72:75], v[158:161], v[206:209], v[72:75]
	v_mfma_f32_16x16x32_bf16 v[124:127], v[154:157], v[186:189], v[124:127]
	v_mfma_f32_16x16x32_bf16 v[120:123], v[162:165], v[186:189], v[120:123]
	v_mfma_f32_16x16x32_bf16 v[108:111], v[154:157], v[194:197], v[108:111]
	v_mfma_f32_16x16x32_bf16 v[104:107], v[162:165], v[194:197], v[104:107]
	v_mfma_f32_16x16x32_bf16 v[92:95], v[154:157], v[202:205], v[92:95]
	v_mfma_f32_16x16x32_bf16 v[88:91], v[162:165], v[202:205], v[88:91]
	v_mfma_f32_16x16x32_bf16 v[76:79], v[154:157], v[210:213], v[76:79]
	v_mfma_f32_16x16x32_bf16 v[72:75], v[162:165], v[210:213], v[72:75]
	v_mfma_f32_16x16x32_bf16 v[116:119], v[166:169], v[182:185], v[116:119]
	v_mfma_f32_16x16x32_bf16 v[112:115], v[174:177], v[182:185], v[112:115]
	v_mfma_f32_16x16x32_bf16 v[100:103], v[166:169], v[190:193], v[100:103]
	v_mfma_f32_16x16x32_bf16 v[96:99], v[174:177], v[190:193], v[96:99]
	v_mfma_f32_16x16x32_bf16 v[84:87], v[166:169], v[198:201], v[84:87]
	v_mfma_f32_16x16x32_bf16 v[80:83], v[174:177], v[198:201], v[80:83]
	v_mfma_f32_16x16x32_bf16 v[68:71], v[166:169], v[206:209], v[68:71]
	v_mfma_f32_16x16x32_bf16 v[64:67], v[174:177], v[206:209], v[64:67]
	v_mfma_f32_16x16x32_bf16 v[116:119], v[170:173], v[186:189], v[116:119]
	v_mfma_f32_16x16x32_bf16 v[112:115], v[178:181], v[186:189], v[112:115]
	v_mfma_f32_16x16x32_bf16 v[100:103], v[170:173], v[194:197], v[100:103]
	v_mfma_f32_16x16x32_bf16 v[96:99], v[178:181], v[194:197], v[96:99]
	v_mfma_f32_16x16x32_bf16 v[84:87], v[170:173], v[202:205], v[84:87]
	v_mfma_f32_16x16x32_bf16 v[80:83], v[178:181], v[202:205], v[80:83]
	v_mfma_f32_16x16x32_bf16 v[68:71], v[170:173], v[210:213], v[68:71]
	v_mfma_f32_16x16x32_bf16 v[64:67], v[178:181], v[210:213], v[64:67]
	s_barrier
	s_add_i32 s38, s63, s47
	v_lshl_add_u64 v[214:215], v[214:215], 0, s[22:23]
	s_mov_b32 m0, s38
	ds_read_b128 v[182:185], v153 offset:49152
	ds_read_b128 v[186:189], v153 offset:50176
	ds_read_b128 v[190:193], v153 offset:51200
	ds_read_b128 v[194:197], v153 offset:52224
	ds_read_b128 v[198:201], v153 offset:53248
	ds_read_b128 v[202:205], v153 offset:54272
	ds_read_b128 v[206:209], v153 offset:55296
	ds_read_b128 v[210:213], v153 offset:56320
	global_load_lds_dwordx4 v[214:215], off
	s_add_i32 m0, s38, 0x2000
	s_add_u32 s38, s42, 0xb0080
	v_lshl_add_u64 v[214:215], v[216:217], 0, s[22:23]
	s_addc_u32 s39, s43, 0
	s_add_i32 s42, s64, s47
	global_load_lds_dwordx4 v[214:215], off
	v_lshl_add_u64 v[214:215], s[38:39], 0, v[130:131]
	s_mov_b32 m0, s42
	s_nop 0
	global_load_lds_dwordx4 v[214:215], off
	v_lshl_add_u64 v[214:215], s[38:39], 0, v[134:135]
	s_add_i32 m0, s42, 0x2000
	s_nop 0
	global_load_lds_dwordx4 v[214:215], off
	v_lshl_add_u64 v[214:215], v[218:219], 0, s[22:23]
	s_mov_b32 m0, s55
	s_nop 0
	global_load_lds_dwordx4 v[214:215], off
	v_lshl_add_u64 v[214:215], v[220:221], 0, s[22:23]
	s_mov_b32 m0, s56
	s_nop 0
	global_load_lds_dwordx4 v[214:215], off
	s_waitcnt vmcnt(8) lgkmcnt(0)
	s_barrier
	v_mfma_f32_16x16x32_bf16 v[60:63], v[144:147], v[182:185], v[60:63]
	v_mfma_f32_16x16x32_bf16 v[56:59], v[158:161], v[182:185], v[56:59]
	v_mfma_f32_16x16x32_bf16 v[44:47], v[144:147], v[190:193], v[44:47]
	v_mfma_f32_16x16x32_bf16 v[40:43], v[158:161], v[190:193], v[40:43]
	v_mfma_f32_16x16x32_bf16 v[28:31], v[144:147], v[198:201], v[28:31]
	v_mfma_f32_16x16x32_bf16 v[24:27], v[158:161], v[198:201], v[24:27]
	v_mfma_f32_16x16x32_bf16 v[12:15], v[144:147], v[206:209], v[12:15]
	v_mfma_f32_16x16x32_bf16 v[8:11], v[158:161], v[206:209], v[8:11]
	v_mfma_f32_16x16x32_bf16 v[60:63], v[154:157], v[186:189], v[60:63]
	v_mfma_f32_16x16x32_bf16 v[56:59], v[162:165], v[186:189], v[56:59]
	v_mfma_f32_16x16x32_bf16 v[44:47], v[154:157], v[194:197], v[44:47]
	v_mfma_f32_16x16x32_bf16 v[40:43], v[162:165], v[194:197], v[40:43]
	v_mfma_f32_16x16x32_bf16 v[28:31], v[154:157], v[202:205], v[28:31]
	v_mfma_f32_16x16x32_bf16 v[24:27], v[162:165], v[202:205], v[24:27]
	v_mfma_f32_16x16x32_bf16 v[12:15], v[154:157], v[210:213], v[12:15]
	v_mfma_f32_16x16x32_bf16 v[8:11], v[162:165], v[210:213], v[8:11]
	v_mfma_f32_16x16x32_bf16 v[52:55], v[166:169], v[182:185], v[52:55]
	v_mfma_f32_16x16x32_bf16 v[48:51], v[174:177], v[182:185], v[48:51]
	v_mfma_f32_16x16x32_bf16 v[36:39], v[166:169], v[190:193], v[36:39]
	v_mfma_f32_16x16x32_bf16 v[32:35], v[174:177], v[190:193], v[32:35]
	v_mfma_f32_16x16x32_bf16 v[20:23], v[166:169], v[198:201], v[20:23]
	v_mfma_f32_16x16x32_bf16 v[16:19], v[174:177], v[198:201], v[16:19]
	v_mfma_f32_16x16x32_bf16 v[4:7], v[166:169], v[206:209], v[4:7]
	v_mfma_f32_16x16x32_bf16 v[0:3], v[174:177], v[206:209], v[0:3]
	v_mfma_f32_16x16x32_bf16 v[52:55], v[170:173], v[186:189], v[52:55]
	v_mfma_f32_16x16x32_bf16 v[48:51], v[178:181], v[186:189], v[48:51]
	v_mfma_f32_16x16x32_bf16 v[36:39], v[170:173], v[194:197], v[36:39]
	v_mfma_f32_16x16x32_bf16 v[32:35], v[178:181], v[194:197], v[32:35]
	v_mfma_f32_16x16x32_bf16 v[20:23], v[170:173], v[202:205], v[20:23]
	v_mfma_f32_16x16x32_bf16 v[16:19], v[178:181], v[202:205], v[16:19]
	v_mfma_f32_16x16x32_bf16 v[4:7], v[170:173], v[210:213], v[4:7]
	v_mfma_f32_16x16x32_bf16 v[0:3], v[178:181], v[210:213], v[0:3]
	s_barrier
	s_add_i32 s62, s62, 2
	s_add_u32 s26, s26, 0x100
	s_addc_u32 s27, s27, 0
	s_cmp_gt_u32 s62, 41
	s_mov_b64 s[38:39], s[40:41]
	s_cbranch_scc0 .LBB0_1835
	s_and_b64 vcc, exec, s[34:35]
	s_cbranch_vccz .LBB0_1838
	s_barrier

.LBB0_1931:
	ds_read_b128 v[144:147], v181
	ds_read_b128 v[148:151], v181 offset:1024
	ds_read_b128 v[152:155], v181 offset:2048
	ds_read_b128 v[156:159], v181 offset:3072
	ds_read_b128 v[160:163], v182
	ds_read_b128 v[164:167], v182 offset:1024
	ds_read_b128 v[168:171], v182 offset:2048
	ds_read_b128 v[172:175], v182 offset:3072
	s_add_u32 s36, s34, 0x100
	s_addc_u32 s37, s35, 0
	s_cmp_eq_u32 s60, 40
	s_cselect_b32 s41, s7, s37
	s_cselect_b32 s40, s6, s36
	s_cselect_b32 s39, s31, s27
	s_cselect_b32 s38, s30, s16
	v_lshl_add_u64 v[176:177], s[34:35], 0, v[138:139]
	s_add_i32 m0, s42, 0xc000
	ds_read_b128 v[186:189], v183
	ds_read_b128 v[190:193], v183 offset:1024
	ds_read_b128 v[194:197], v183 offset:2048
	ds_read_b128 v[198:201], v183 offset:3072
	ds_read_b128 v[202:205], v183 offset:4096
	ds_read_b128 v[206:209], v183 offset:5120
	ds_read_b128 v[210:213], v183 offset:6144
	ds_read_b128 v[214:217], v183 offset:7168
	global_load_lds_dwordx4 v[176:177], off
	v_lshl_add_u64 v[176:177], s[34:35], 0, v[136:137]
	s_add_i32 m0, s42, 0xe000
	s_nop 0
	global_load_lds_dwordx4 v[176:177], off
	s_waitcnt vmcnt(8) lgkmcnt(0)
	s_barrier
	v_mfma_f32_16x16x32_bf16 v[124:127], v[144:147], v[186:189], v[124:127]
	v_mfma_f32_16x16x32_bf16 v[120:123], v[152:155], v[186:189], v[120:123]
	v_mfma_f32_16x16x32_bf16 v[108:111], v[144:147], v[194:197], v[108:111]
	v_mfma_f32_16x16x32_bf16 v[104:107], v[152:155], v[194:197], v[104:107]
	v_mfma_f32_16x16x32_bf16 v[92:95], v[144:147], v[202:205], v[92:95]
	v_mfma_f32_16x16x32_bf16 v[88:91], v[152:155], v[202:205], v[88:91]
	v_mfma_f32_16x16x32_bf16 v[76:79], v[144:147], v[210:213], v[76:79]
	v_mfma_f32_16x16x32_bf16 v[72:75], v[152:155], v[210:213], v[72:75]
	v_mfma_f32_16x16x32_bf16 v[124:127], v[148:151], v[190:193], v[124:127]
	v_mfma_f32_16x16x32_bf16 v[120:123], v[156:159], v[190:193], v[120:123]
	v_mfma_f32_16x16x32_bf16 v[108:111], v[148:151], v[198:201], v[108:111]
	v_mfma_f32_16x16x32_bf16 v[104:107], v[156:159], v[198:201], v[104:107]
	v_mfma_f32_16x16x32_bf16 v[92:95], v[148:151], v[206:209], v[92:95]
	v_mfma_f32_16x16x32_bf16 v[88:91], v[156:159], v[206:209], v[88:91]
	v_mfma_f32_16x16x32_bf16 v[76:79], v[148:151], v[214:217], v[76:79]
	v_mfma_f32_16x16x32_bf16 v[72:75], v[156:159], v[214:217], v[72:75]
	v_mfma_f32_16x16x32_bf16 v[116:119], v[160:163], v[186:189], v[116:119]
	v_mfma_f32_16x16x32_bf16 v[112:115], v[168:171], v[186:189], v[112:115]
	v_mfma_f32_16x16x32_bf16 v[100:103], v[160:163], v[194:197], v[100:103]
	v_mfma_f32_16x16x32_bf16 v[96:99], v[168:171], v[194:197], v[96:99]
	v_mfma_f32_16x16x32_bf16 v[84:87], v[160:163], v[202:205], v[84:87]
	v_mfma_f32_16x16x32_bf16 v[80:83], v[168:171], v[202:205], v[80:83]
	v_mfma_f32_16x16x32_bf16 v[68:71], v[160:163], v[210:213], v[68:71]
	v_mfma_f32_16x16x32_bf16 v[64:67], v[168:171], v[210:213], v[64:67]
	v_mfma_f32_16x16x32_bf16 v[116:119], v[164:167], v[190:193], v[116:119]
	v_mfma_f32_16x16x32_bf16 v[112:115], v[172:175], v[190:193], v[112:115]
	v_mfma_f32_16x16x32_bf16 v[100:103], v[164:167], v[198:201], v[100:103]
	v_mfma_f32_16x16x32_bf16 v[96:99], v[172:175], v[198:201], v[96:99]
	v_mfma_f32_16x16x32_bf16 v[84:87], v[164:167], v[206:209], v[84:87]
	v_mfma_f32_16x16x32_bf16 v[80:83], v[172:175], v[206:209], v[80:83]
	v_mfma_f32_16x16x32_bf16 v[68:71], v[164:167], v[214:217], v[68:71]
	v_mfma_f32_16x16x32_bf16 v[64:67], v[172:175], v[214:217], v[64:67]
	s_barrier
	s_add_i32 s34, s54, s25
	v_lshl_add_u64 v[176:177], s[38:39], 0, v[130:131]
	s_mov_b32 m0, s34
	ds_read_b128 v[186:189], v183 offset:16384
	ds_read_b128 v[190:193], v183 offset:17408
	ds_read_b128 v[194:197], v183 offset:18432
	ds_read_b128 v[198:201], v183 offset:19456
	ds_read_b128 v[202:205], v183 offset:20480
	ds_read_b128 v[206:209], v183 offset:21504
	ds_read_b128 v[210:213], v183 offset:22528
	ds_read_b128 v[214:217], v183 offset:23552
	global_load_lds_dwordx4 v[176:177], off
	s_add_i32 m0, s34, 0x2000
	s_add_u32 s34, s38, 0xb0000
	v_lshl_add_u64 v[218:219], s[38:39], 0, v[134:135]
	s_addc_u32 s35, s39, 0
	s_add_i32 s61, s55, s25
	global_load_lds_dwordx4 v[218:219], off
	v_lshl_add_u64 v[220:221], s[34:35], 0, v[130:131]
	s_mov_b32 m0, s61
	v_lshl_add_u64 v[222:223], s[40:41], 0, v[132:133]
	global_load_lds_dwordx4 v[220:221], off
	v_lshl_add_u64 v[220:221], s[34:35], 0, v[134:135]
	s_add_i32 m0, s61, 0x2000
	s_nop 0
	global_load_lds_dwordx4 v[220:221], off
	v_lshl_add_u64 v[220:221], s[40:41], 0, v[128:129]
	s_mov_b32 m0, s42
	s_nop 0
	global_load_lds_dwordx4 v[220:221], off
	s_mov_b32 m0, s43
	s_nop 0
	global_load_lds_dwordx4 v[222:223], off
	s_waitcnt vmcnt(8) lgkmcnt(0)
	s_barrier
	v_mfma_f32_16x16x32_bf16 v[60:63], v[144:147], v[186:189], v[60:63]
	v_mfma_f32_16x16x32_bf16 v[56:59], v[152:155], v[186:189], v[56:59]
	v_mfma_f32_16x16x32_bf16 v[44:47], v[144:147], v[194:197], v[44:47]
	v_mfma_f32_16x16x32_bf16 v[40:43], v[152:155], v[194:197], v[40:43]
	v_mfma_f32_16x16x32_bf16 v[28:31], v[144:147], v[202:205], v[28:31]
	v_mfma_f32_16x16x32_bf16 v[24:27], v[152:155], v[202:205], v[24:27]
	v_mfma_f32_16x16x32_bf16 v[12:15], v[144:147], v[210:213], v[12:15]
	v_mfma_f32_16x16x32_bf16 v[8:11], v[152:155], v[210:213], v[8:11]
	v_mfma_f32_16x16x32_bf16 v[60:63], v[148:151], v[190:193], v[60:63]
	v_mfma_f32_16x16x32_bf16 v[56:59], v[156:159], v[190:193], v[56:59]
	v_mfma_f32_16x16x32_bf16 v[44:47], v[148:151], v[198:201], v[44:47]
	v_mfma_f32_16x16x32_bf16 v[40:43], v[156:159], v[198:201], v[40:43]
	v_mfma_f32_16x16x32_bf16 v[28:31], v[148:151], v[206:209], v[28:31]
	v_mfma_f32_16x16x32_bf16 v[24:27], v[156:159], v[206:209], v[24:27]
	v_mfma_f32_16x16x32_bf16 v[12:15], v[148:151], v[214:217], v[12:15]
	v_mfma_f32_16x16x32_bf16 v[8:11], v[156:159], v[214:217], v[8:11]
	v_mfma_f32_16x16x32_bf16 v[52:55], v[160:163], v[186:189], v[52:55]
	v_mfma_f32_16x16x32_bf16 v[48:51], v[168:171], v[186:189], v[48:51]
	v_mfma_f32_16x16x32_bf16 v[36:39], v[160:163], v[194:197], v[36:39]
	v_mfma_f32_16x16x32_bf16 v[32:35], v[168:171], v[194:197], v[32:35]
	v_mfma_f32_16x16x32_bf16 v[20:23], v[160:163], v[202:205], v[20:23]
	v_mfma_f32_16x16x32_bf16 v[16:19], v[168:171], v[202:205], v[16:19]
	v_mfma_f32_16x16x32_bf16 v[4:7], v[160:163], v[210:213], v[4:7]
	v_mfma_f32_16x16x32_bf16 v[0:3], v[168:171], v[210:213], v[0:3]
	v_mfma_f32_16x16x32_bf16 v[52:55], v[164:167], v[190:193], v[52:55]
	v_mfma_f32_16x16x32_bf16 v[48:51], v[172:175], v[190:193], v[48:51]
	v_mfma_f32_16x16x32_bf16 v[36:39], v[164:167], v[198:201], v[36:39]
	v_mfma_f32_16x16x32_bf16 v[32:35], v[172:175], v[198:201], v[32:35]
	v_mfma_f32_16x16x32_bf16 v[20:23], v[164:167], v[206:209], v[20:23]
	v_mfma_f32_16x16x32_bf16 v[16:19], v[172:175], v[206:209], v[16:19]
	v_mfma_f32_16x16x32_bf16 v[4:7], v[164:167], v[214:217], v[4:7]
	v_mfma_f32_16x16x32_bf16 v[0:3], v[172:175], v[214:217], v[0:3]
	s_barrier
	s_add_i32 s61, 0, 0x18000
	s_add_i32 s62, 0, 0x1c000
	v_add_u32_e32 v156, s61, v180
	v_add_u32_e32 v172, s62, v180
	ds_read_b128 v[144:147], v156
	ds_read_b128 v[148:151], v156 offset:1024
	ds_read_b128 v[152:155], v156 offset:2048
	ds_read_b128 v[156:159], v156 offset:3072
	ds_read_b128 v[160:163], v172
	ds_read_b128 v[164:167], v172 offset:1024
	ds_read_b128 v[168:171], v172 offset:2048
	ds_read_b128 v[172:175], v172 offset:3072
	s_add_u32 s34, s40, 0xb0000
	s_addc_u32 s35, s41, 0
	s_mov_b32 m0, s44
	v_lshl_add_u64 v[226:227], s[34:35], 0, v[128:129]
	ds_read_b128 v[186:189], v183 offset:32768
	ds_read_b128 v[190:193], v183 offset:33792
	ds_read_b128 v[194:197], v183 offset:34816
	ds_read_b128 v[198:201], v183 offset:35840
	ds_read_b128 v[202:205], v183 offset:36864
	ds_read_b128 v[206:209], v183 offset:37888
	ds_read_b128 v[210:213], v183 offset:38912
	ds_read_b128 v[214:217], v183 offset:39936
	global_load_lds_dwordx4 v[226:227], off
	v_lshl_add_u64 v[226:227], s[34:35], 0, v[132:133]
	s_mov_b32 m0, s45
	s_nop 0
	global_load_lds_dwordx4 v[226:227], off
	s_waitcnt vmcnt(8) lgkmcnt(0)
	s_barrier
	v_mfma_f32_16x16x32_bf16 v[124:127], v[144:147], v[186:189], v[124:127]
	v_mfma_f32_16x16x32_bf16 v[120:123], v[152:155], v[186:189], v[120:123]
	v_mfma_f32_16x16x32_bf16 v[108:111], v[144:147], v[194:197], v[108:111]
	v_mfma_f32_16x16x32_bf16 v[104:107], v[152:155], v[194:197], v[104:107]
	v_mfma_f32_16x16x32_bf16 v[92:95], v[144:147], v[202:205], v[92:95]
	v_mfma_f32_16x16x32_bf16 v[88:91], v[152:155], v[202:205], v[88:91]
	v_mfma_f32_16x16x32_bf16 v[76:79], v[144:147], v[210:213], v[76:79]
	v_mfma_f32_16x16x32_bf16 v[72:75], v[152:155], v[210:213], v[72:75]
	v_mfma_f32_16x16x32_bf16 v[124:127], v[148:151], v[190:193], v[124:127]
	v_mfma_f32_16x16x32_bf16 v[120:123], v[156:159], v[190:193], v[120:123]
	v_mfma_f32_16x16x32_bf16 v[108:111], v[148:151], v[198:201], v[108:111]
	v_mfma_f32_16x16x32_bf16 v[104:107], v[156:159], v[198:201], v[104:107]
	v_mfma_f32_16x16x32_bf16 v[92:95], v[148:151], v[206:209], v[92:95]
	v_mfma_f32_16x16x32_bf16 v[88:91], v[156:159], v[206:209], v[88:91]
	v_mfma_f32_16x16x32_bf16 v[76:79], v[148:151], v[214:217], v[76:79]
	v_mfma_f32_16x16x32_bf16 v[72:75], v[156:159], v[214:217], v[72:75]
	v_mfma_f32_16x16x32_bf16 v[116:119], v[160:163], v[186:189], v[116:119]
	v_mfma_f32_16x16x32_bf16 v[112:115], v[168:171], v[186:189], v[112:115]
	v_mfma_f32_16x16x32_bf16 v[100:103], v[160:163], v[194:197], v[100:103]
	v_mfma_f32_16x16x32_bf16 v[96:99], v[168:171], v[194:197], v[96:99]
	v_mfma_f32_16x16x32_bf16 v[84:87], v[160:163], v[202:205], v[84:87]
	v_mfma_f32_16x16x32_bf16 v[80:83], v[168:171], v[202:205], v[80:83]
	v_mfma_f32_16x16x32_bf16 v[68:71], v[160:163], v[210:213], v[68:71]
	v_mfma_f32_16x16x32_bf16 v[64:67], v[168:171], v[210:213], v[64:67]
	v_mfma_f32_16x16x32_bf16 v[116:119], v[164:167], v[190:193], v[116:119]
	v_mfma_f32_16x16x32_bf16 v[112:115], v[172:175], v[190:193], v[112:115]
	v_mfma_f32_16x16x32_bf16 v[100:103], v[164:167], v[198:201], v[100:103]
	v_mfma_f32_16x16x32_bf16 v[96:99], v[172:175], v[198:201], v[96:99]
	v_mfma_f32_16x16x32_bf16 v[84:87], v[164:167], v[206:209], v[84:87]
	v_mfma_f32_16x16x32_bf16 v[80:83], v[172:175], v[206:209], v[80:83]
	v_mfma_f32_16x16x32_bf16 v[68:71], v[164:167], v[214:217], v[68:71]
	v_mfma_f32_16x16x32_bf16 v[64:67], v[172:175], v[214:217], v[64:67]
	s_barrier
	s_add_i32 s34, s61, s25
	v_lshl_add_u64 v[176:177], v[176:177], 0, s[20:21]
	s_mov_b32 m0, s34
	ds_read_b128 v[186:189], v183 offset:49152
	ds_read_b128 v[190:193], v183 offset:50176
	ds_read_b128 v[194:197], v183 offset:51200
	ds_read_b128 v[198:201], v183 offset:52224
	ds_read_b128 v[202:205], v183 offset:53248
	ds_read_b128 v[206:209], v183 offset:54272
	ds_read_b128 v[210:213], v183 offset:55296
	ds_read_b128 v[214:217], v183 offset:56320
	global_load_lds_dwordx4 v[176:177], off
	s_add_i32 m0, s34, 0x2000
	s_add_u32 s34, s38, 0xb0080
	v_lshl_add_u64 v[176:177], v[218:219], 0, s[20:21]
	s_addc_u32 s35, s39, 0
	s_add_i32 s38, s62, s25
	global_load_lds_dwordx4 v[176:177], off
	v_lshl_add_u64 v[176:177], s[34:35], 0, v[130:131]
	s_mov_b32 m0, s38
	s_nop 0
	global_load_lds_dwordx4 v[176:177], off
	v_lshl_add_u64 v[176:177], s[34:35], 0, v[134:135]
	s_add_i32 m0, s38, 0x2000
	s_nop 0
	global_load_lds_dwordx4 v[176:177], off
	v_lshl_add_u64 v[176:177], v[220:221], 0, s[20:21]
	s_mov_b32 m0, s51
	s_nop 0
	global_load_lds_dwordx4 v[176:177], off
	v_lshl_add_u64 v[176:177], v[222:223], 0, s[20:21]
	s_mov_b32 m0, s52
	s_nop 0
	global_load_lds_dwordx4 v[176:177], off
	s_waitcnt vmcnt(8) lgkmcnt(0)
	s_barrier
	v_mfma_f32_16x16x32_bf16 v[60:63], v[144:147], v[186:189], v[60:63]
	v_mfma_f32_16x16x32_bf16 v[56:59], v[152:155], v[186:189], v[56:59]
	v_mfma_f32_16x16x32_bf16 v[44:47], v[144:147], v[194:197], v[44:47]
	v_mfma_f32_16x16x32_bf16 v[40:43], v[152:155], v[194:197], v[40:43]
	v_mfma_f32_16x16x32_bf16 v[28:31], v[144:147], v[202:205], v[28:31]
	v_mfma_f32_16x16x32_bf16 v[24:27], v[152:155], v[202:205], v[24:27]
	v_mfma_f32_16x16x32_bf16 v[12:15], v[144:147], v[210:213], v[12:15]
	v_mfma_f32_16x16x32_bf16 v[8:11], v[152:155], v[210:213], v[8:11]
	v_mfma_f32_16x16x32_bf16 v[60:63], v[148:151], v[190:193], v[60:63]
	v_mfma_f32_16x16x32_bf16 v[56:59], v[156:159], v[190:193], v[56:59]
	v_mfma_f32_16x16x32_bf16 v[44:47], v[148:151], v[198:201], v[44:47]
	v_mfma_f32_16x16x32_bf16 v[40:43], v[156:159], v[198:201], v[40:43]
	v_mfma_f32_16x16x32_bf16 v[28:31], v[148:151], v[206:209], v[28:31]
	v_mfma_f32_16x16x32_bf16 v[24:27], v[156:159], v[206:209], v[24:27]
	v_mfma_f32_16x16x32_bf16 v[12:15], v[148:151], v[214:217], v[12:15]
	v_mfma_f32_16x16x32_bf16 v[8:11], v[156:159], v[214:217], v[8:11]
	v_mfma_f32_16x16x32_bf16 v[52:55], v[160:163], v[186:189], v[52:55]
	v_mfma_f32_16x16x32_bf16 v[48:51], v[168:171], v[186:189], v[48:51]
	v_mfma_f32_16x16x32_bf16 v[36:39], v[160:163], v[194:197], v[36:39]
	v_mfma_f32_16x16x32_bf16 v[32:35], v[168:171], v[194:197], v[32:35]
	v_mfma_f32_16x16x32_bf16 v[20:23], v[160:163], v[202:205], v[20:23]
	v_mfma_f32_16x16x32_bf16 v[16:19], v[168:171], v[202:205], v[16:19]
	v_mfma_f32_16x16x32_bf16 v[4:7], v[160:163], v[210:213], v[4:7]
	v_mfma_f32_16x16x32_bf16 v[0:3], v[168:171], v[210:213], v[0:3]
	v_mfma_f32_16x16x32_bf16 v[52:55], v[164:167], v[190:193], v[52:55]
	v_mfma_f32_16x16x32_bf16 v[48:51], v[172:175], v[190:193], v[48:51]
	v_mfma_f32_16x16x32_bf16 v[36:39], v[164:167], v[198:201], v[36:39]
	v_mfma_f32_16x16x32_bf16 v[32:35], v[172:175], v[198:201], v[32:35]
	v_mfma_f32_16x16x32_bf16 v[20:23], v[164:167], v[206:209], v[20:23]
	v_mfma_f32_16x16x32_bf16 v[16:19], v[172:175], v[206:209], v[16:19]
	v_mfma_f32_16x16x32_bf16 v[4:7], v[164:167], v[214:217], v[4:7]
	v_mfma_f32_16x16x32_bf16 v[0:3], v[172:175], v[214:217], v[0:3]
	s_barrier
	s_add_i32 s60, s60, 2
	s_add_u32 s16, s16, 0x100
	s_addc_u32 s27, s27, 0
	s_cmp_gt_u32 s60, 41
	s_mov_b64 s[34:35], s[36:37]
	s_cbranch_scc0 .LBB0_1931
	s_and_b64 vcc, exec, s[22:23]
	s_cbranch_vccz .LBB0_1934
	s_barrier
